# GEMM K-loops: s_nop before each LDS-DMA removed by placing the address add between the m0 write and the load (37 sites)
# baseline (speedup 1.0000x reference)
.LBB0_173:
	s_add_u32 s64, s62, 0x100
	s_addc_u32 s65, s63, 0
	s_add_i32 s34, 0, 0x10000
	v_add_u32_e32 v108, s34, v196
	ds_read_b128 v[96:99], v108
	ds_read_b128 v[100:103], v108 offset:1024
	ds_read_b128 v[104:107], v108 offset:2048
	ds_read_b128 v[158:161], v108 offset:3072
	s_cmp_eq_u32 s83, 28
	s_cselect_b32 s69, s57, s65
	s_cselect_b32 s68, s71, s64
	s_cselect_b32 s67, s55, s82
	s_cselect_b32 s66, s80, s81
	v_lshl_add_u64 v[108:109], s[62:63], 0, v[154:155]
	s_add_i32 m0, s44, 0xc000
	ds_read_b128 v[162:165], v207
	ds_read_b128 v[166:169], v207 offset:1024
	ds_read_b128 v[170:173], v207 offset:2048
	ds_read_b128 v[180:183], v207 offset:3072
	ds_read_b128 v[184:187], v207 offset:4096
	ds_read_b128 v[188:191], v207 offset:5120
	ds_read_b128 v[192:195], v207 offset:6144
	ds_read_b128 v[198:201], v207 offset:7168
	global_load_lds_dwordx4 v[108:109], off
	s_add_i32 m0, s44, 0xe000
	v_lshl_add_u64 v[108:109], s[62:63], 0, v[156:157]
	global_load_lds_dwordx4 v[108:109], off
	s_waitcnt lgkmcnt(8)
	s_barrier
	s_waitcnt lgkmcnt(0)
	v_mfma_f32_16x16x32_bf16 v[138:141], v[96:99], v[162:165], v[138:141]
	v_mfma_f32_16x16x32_bf16 v[60:63], v[104:107], v[162:165], v[60:63]
	v_mfma_f32_16x16x32_bf16 v[134:137], v[96:99], v[170:173], v[134:137]
	v_mfma_f32_16x16x32_bf16 v[56:59], v[104:107], v[170:173], v[56:59]
	v_mfma_f32_16x16x32_bf16 v[130:133], v[96:99], v[184:187], v[130:133]
	v_mfma_f32_16x16x32_bf16 v[52:55], v[104:107], v[184:187], v[52:55]
	v_mfma_f32_16x16x32_bf16 v[126:129], v[96:99], v[192:195], v[126:129]
	v_mfma_f32_16x16x32_bf16 v[48:51], v[104:107], v[192:195], v[48:51]
	v_mfma_f32_16x16x32_bf16 v[138:141], v[100:103], v[166:169], v[138:141]
	v_mfma_f32_16x16x32_bf16 v[60:63], v[158:161], v[166:169], v[60:63]
	v_mfma_f32_16x16x32_bf16 v[134:137], v[100:103], v[180:183], v[134:137]
	v_mfma_f32_16x16x32_bf16 v[56:59], v[158:161], v[180:183], v[56:59]
	v_mfma_f32_16x16x32_bf16 v[130:133], v[100:103], v[188:191], v[130:133]
	v_mfma_f32_16x16x32_bf16 v[52:55], v[158:161], v[188:191], v[52:55]
	v_mfma_f32_16x16x32_bf16 v[126:129], v[100:103], v[198:201], v[126:129]
	v_mfma_f32_16x16x32_bf16 v[48:51], v[158:161], v[198:201], v[48:51]
	s_barrier
	s_add_i32 s35, 0, 0x14000
	s_add_i32 s34, s34, s39
	v_add_u32_e32 v108, s35, v196
	v_lshl_add_u64 v[174:175], s[66:67], 0, v[146:147]
	s_mov_b32 m0, s34
	ds_read_b128 v[208:211], v108
	ds_read_b128 v[212:215], v108 offset:1024
	ds_read_b128 v[216:219], v108 offset:2048
	ds_read_b128 v[220:223], v108 offset:3072
	global_load_lds_dwordx4 v[174:175], off
	s_add_i32 m0, s34, 0x2000
	v_lshl_add_u64 v[224:225], s[66:67], 0, v[142:143]
	global_load_lds_dwordx4 v[224:225], off
	s_barrier
	s_waitcnt lgkmcnt(0)
	v_mfma_f32_16x16x32_bf16 v[122:125], v[208:211], v[162:165], v[122:125]
	v_mfma_f32_16x16x32_bf16 v[44:47], v[216:219], v[162:165], v[44:47]
	v_mfma_f32_16x16x32_bf16 v[114:117], v[208:211], v[170:173], v[114:117]
	v_mfma_f32_16x16x32_bf16 v[36:39], v[216:219], v[170:173], v[36:39]
	v_mfma_f32_16x16x32_bf16 v[118:121], v[208:211], v[184:187], v[118:121]
	v_mfma_f32_16x16x32_bf16 v[40:43], v[216:219], v[184:187], v[40:43]
	v_mfma_f32_16x16x32_bf16 v[108:111], v[208:211], v[192:195], v[110:113]
	v_mfma_f32_16x16x32_bf16 v[32:35], v[216:219], v[192:195], v[32:35]
	v_mfma_f32_16x16x32_bf16 v[122:125], v[212:215], v[166:169], v[122:125]
	v_mfma_f32_16x16x32_bf16 v[44:47], v[220:223], v[166:169], v[44:47]
	v_mfma_f32_16x16x32_bf16 v[114:117], v[212:215], v[180:183], v[114:117]
	v_mfma_f32_16x16x32_bf16 v[36:39], v[220:223], v[180:183], v[36:39]
	v_mfma_f32_16x16x32_bf16 v[118:121], v[212:215], v[188:191], v[118:121]
	v_mfma_f32_16x16x32_bf16 v[40:43], v[220:223], v[188:191], v[40:43]
	v_mfma_f32_16x16x32_bf16 v[108:111], v[212:215], v[198:201], v[108:111]
	v_mfma_f32_16x16x32_bf16 v[32:35], v[220:223], v[198:201], v[32:35]
	s_mov_b32 m0, s44
	v_lshl_add_u64 v[226:227], s[68:69], 0, v[148:149]
	s_barrier
	ds_read_b128 v[162:165], v207 offset:16384
	ds_read_b128 v[166:169], v207 offset:17408
	ds_read_b128 v[170:173], v207 offset:18432
	ds_read_b128 v[180:183], v207 offset:19456
	ds_read_b128 v[184:187], v207 offset:20480
	ds_read_b128 v[188:191], v207 offset:21504
	ds_read_b128 v[192:195], v207 offset:22528
	ds_read_b128 v[198:201], v207 offset:23552
	global_load_lds_dwordx4 v[226:227], off
	s_mov_b32 m0, s72
	v_lshl_add_u64 v[228:229], s[68:69], 0, v[144:145]
	global_load_lds_dwordx4 v[228:229], off
	s_barrier
	s_waitcnt lgkmcnt(0)
	v_mfma_f32_16x16x32_bf16 v[92:95], v[96:99], v[162:165], v[92:95]
	v_mfma_f32_16x16x32_bf16 v[28:31], v[104:107], v[162:165], v[28:31]
	v_mfma_f32_16x16x32_bf16 v[88:91], v[96:99], v[170:173], v[88:91]
	v_mfma_f32_16x16x32_bf16 v[24:27], v[104:107], v[170:173], v[24:27]
	v_mfma_f32_16x16x32_bf16 v[84:87], v[96:99], v[184:187], v[84:87]
	v_mfma_f32_16x16x32_bf16 v[20:23], v[104:107], v[184:187], v[20:23]
	v_mfma_f32_16x16x32_bf16 v[80:83], v[96:99], v[192:195], v[80:83]
	v_mfma_f32_16x16x32_bf16 v[16:19], v[104:107], v[192:195], v[16:19]
	v_mfma_f32_16x16x32_bf16 v[92:95], v[100:103], v[166:169], v[92:95]
	v_mfma_f32_16x16x32_bf16 v[28:31], v[158:161], v[166:169], v[28:31]
	v_mfma_f32_16x16x32_bf16 v[88:91], v[100:103], v[180:183], v[88:91]
	v_mfma_f32_16x16x32_bf16 v[24:27], v[158:161], v[180:183], v[24:27]
	v_mfma_f32_16x16x32_bf16 v[84:87], v[100:103], v[188:191], v[84:87]
	v_mfma_f32_16x16x32_bf16 v[20:23], v[158:161], v[188:191], v[20:23]
	v_mfma_f32_16x16x32_bf16 v[80:83], v[100:103], v[198:201], v[80:83]
	v_mfma_f32_16x16x32_bf16 v[16:19], v[158:161], v[198:201], v[16:19]
	s_barrier
	s_add_u32 s62, s66, 0x80000
	s_addc_u32 s63, s67, 0
	s_add_i32 s34, s35, s39
	s_mov_b32 m0, s34
	v_lshl_add_u64 v[96:97], s[62:63], 0, v[146:147]
	global_load_lds_dwordx4 v[96:97], off
	s_add_i32 m0, s34, 0x2000
	v_lshl_add_u64 v[96:97], s[62:63], 0, v[142:143]
	global_load_lds_dwordx4 v[96:97], off
	s_waitcnt vmcnt(6)
	s_barrier
	v_mfma_f32_16x16x32_bf16 v[76:79], v[208:211], v[162:165], v[76:79]
	v_mfma_f32_16x16x32_bf16 v[12:15], v[216:219], v[162:165], v[12:15]
	v_mfma_f32_16x16x32_bf16 v[68:71], v[208:211], v[170:173], v[68:71]
	v_mfma_f32_16x16x32_bf16 v[4:7], v[216:219], v[170:173], v[4:7]
	v_mfma_f32_16x16x32_bf16 v[72:75], v[208:211], v[184:187], v[72:75]
	v_mfma_f32_16x16x32_bf16 v[8:11], v[216:219], v[184:187], v[8:11]
	v_mfma_f32_16x16x32_bf16 v[64:67], v[208:211], v[192:195], v[64:67]
	v_mfma_f32_16x16x32_bf16 v[0:3], v[216:219], v[192:195], v[0:3]
	v_mfma_f32_16x16x32_bf16 v[76:79], v[212:215], v[166:169], v[76:79]
	v_mfma_f32_16x16x32_bf16 v[12:15], v[220:223], v[166:169], v[12:15]
	v_mfma_f32_16x16x32_bf16 v[68:71], v[212:215], v[180:183], v[68:71]
	v_mfma_f32_16x16x32_bf16 v[4:7], v[220:223], v[180:183], v[4:7]
	v_mfma_f32_16x16x32_bf16 v[72:75], v[212:215], v[188:191], v[72:75]
	v_mfma_f32_16x16x32_bf16 v[8:11], v[220:223], v[188:191], v[8:11]
	v_mfma_f32_16x16x32_bf16 v[64:67], v[212:215], v[198:201], v[64:67]
	v_mfma_f32_16x16x32_bf16 v[0:3], v[220:223], v[198:201], v[0:3]
	s_add_i32 s34, 0, 0x18000
	v_add_u32_e32 v112, s34, v196
	s_barrier
	ds_read_b128 v[96:99], v112
	ds_read_b128 v[100:103], v112 offset:1024
	ds_read_b128 v[104:107], v112 offset:2048
	ds_read_b128 v[158:161], v112 offset:3072
	s_add_u32 s62, s68, 0x80000
	s_addc_u32 s63, s69, 0
	s_mov_b32 m0, s73
	v_lshl_add_u64 v[112:113], s[62:63], 0, v[148:149]
	ds_read_b128 v[162:165], v207 offset:32768
	ds_read_b128 v[166:169], v207 offset:33792
	ds_read_b128 v[170:173], v207 offset:34816
	ds_read_b128 v[180:183], v207 offset:35840
	ds_read_b128 v[184:187], v207 offset:36864
	ds_read_b128 v[188:191], v207 offset:37888
	ds_read_b128 v[192:195], v207 offset:38912
	ds_read_b128 v[198:201], v207 offset:39936
	global_load_lds_dwordx4 v[112:113], off
	s_mov_b32 m0, s74
	v_lshl_add_u64 v[112:113], s[62:63], 0, v[144:145]
	global_load_lds_dwordx4 v[112:113], off
	s_waitcnt lgkmcnt(8)
	s_barrier
	s_waitcnt lgkmcnt(0)
	v_mfma_f32_16x16x32_bf16 v[138:141], v[96:99], v[162:165], v[138:141]
	v_mfma_f32_16x16x32_bf16 v[60:63], v[104:107], v[162:165], v[60:63]
	v_mfma_f32_16x16x32_bf16 v[134:137], v[96:99], v[170:173], v[134:137]
	v_mfma_f32_16x16x32_bf16 v[56:59], v[104:107], v[170:173], v[56:59]
	v_mfma_f32_16x16x32_bf16 v[130:133], v[96:99], v[184:187], v[130:133]
	v_mfma_f32_16x16x32_bf16 v[52:55], v[104:107], v[184:187], v[52:55]
	v_mfma_f32_16x16x32_bf16 v[126:129], v[96:99], v[192:195], v[126:129]
	v_mfma_f32_16x16x32_bf16 v[48:51], v[104:107], v[192:195], v[48:51]
	v_mfma_f32_16x16x32_bf16 v[138:141], v[100:103], v[166:169], v[138:141]
	v_mfma_f32_16x16x32_bf16 v[60:63], v[158:161], v[166:169], v[60:63]
	v_mfma_f32_16x16x32_bf16 v[134:137], v[100:103], v[180:183], v[134:137]
	v_mfma_f32_16x16x32_bf16 v[56:59], v[158:161], v[180:183], v[56:59]
	v_mfma_f32_16x16x32_bf16 v[130:133], v[100:103], v[188:191], v[130:133]
	v_mfma_f32_16x16x32_bf16 v[52:55], v[158:161], v[188:191], v[52:55]
	v_mfma_f32_16x16x32_bf16 v[126:129], v[100:103], v[198:201], v[126:129]
	v_mfma_f32_16x16x32_bf16 v[48:51], v[158:161], v[198:201], v[48:51]
	s_barrier
	s_add_i32 s35, 0, 0x1c000
	v_add_u32_e32 v112, s35, v196
	s_add_i32 s34, s34, s39
	ds_read_b128 v[208:211], v112
	ds_read_b128 v[212:215], v112 offset:1024
	ds_read_b128 v[216:219], v112 offset:2048
	ds_read_b128 v[220:223], v112 offset:3072
	s_mov_b32 m0, s34
	v_lshl_add_u64 v[112:113], v[174:175], 0, s[40:41]
	global_load_lds_dwordx4 v[112:113], off
	s_add_i32 m0, s34, 0x2000
	v_lshl_add_u64 v[112:113], v[224:225], 0, s[40:41]
	global_load_lds_dwordx4 v[112:113], off
	s_barrier
	s_waitcnt lgkmcnt(0)
	v_mfma_f32_16x16x32_bf16 v[122:125], v[208:211], v[162:165], v[122:125]
	v_mfma_f32_16x16x32_bf16 v[44:47], v[216:219], v[162:165], v[44:47]
	v_mfma_f32_16x16x32_bf16 v[112:115], v[208:211], v[170:173], v[114:117]
	v_mfma_f32_16x16x32_bf16 v[36:39], v[216:219], v[170:173], v[36:39]
	v_mfma_f32_16x16x32_bf16 v[118:121], v[208:211], v[184:187], v[118:121]
	v_mfma_f32_16x16x32_bf16 v[40:43], v[216:219], v[184:187], v[40:43]
	v_mfma_f32_16x16x32_bf16 v[108:111], v[208:211], v[192:195], v[108:111]
	v_mfma_f32_16x16x32_bf16 v[32:35], v[216:219], v[192:195], v[32:35]
	v_mfma_f32_16x16x32_bf16 v[122:125], v[212:215], v[166:169], v[122:125]
	v_mfma_f32_16x16x32_bf16 v[44:47], v[220:223], v[166:169], v[44:47]
	v_mfma_f32_16x16x32_bf16 v[114:117], v[212:215], v[180:183], v[112:115]
	v_mfma_f32_16x16x32_bf16 v[36:39], v[220:223], v[180:183], v[36:39]
	v_mfma_f32_16x16x32_bf16 v[118:121], v[212:215], v[188:191], v[118:121]
	v_mfma_f32_16x16x32_bf16 v[40:43], v[220:223], v[188:191], v[40:43]
	v_mfma_f32_16x16x32_bf16 v[110:113], v[212:215], v[198:201], v[108:111]
	v_mfma_f32_16x16x32_bf16 v[32:35], v[220:223], v[198:201], v[32:35]
	s_barrier
	s_mov_b32 m0, s76
	v_lshl_add_u64 v[108:109], v[226:227], 0, s[40:41]
	ds_read_b128 v[162:165], v207 offset:49152
	ds_read_b128 v[166:169], v207 offset:50176
	ds_read_b128 v[170:173], v207 offset:51200
	ds_read_b128 v[180:183], v207 offset:52224
	ds_read_b128 v[184:187], v207 offset:53248
	ds_read_b128 v[188:191], v207 offset:54272
	ds_read_b128 v[192:195], v207 offset:55296
	ds_read_b128 v[198:201], v207 offset:56320
	global_load_lds_dwordx4 v[108:109], off
	s_mov_b32 m0, s77
	v_lshl_add_u64 v[108:109], v[228:229], 0, s[40:41]
	global_load_lds_dwordx4 v[108:109], off
	s_barrier
	s_waitcnt lgkmcnt(0)
	v_mfma_f32_16x16x32_bf16 v[92:95], v[96:99], v[162:165], v[92:95]
	v_mfma_f32_16x16x32_bf16 v[28:31], v[104:107], v[162:165], v[28:31]
	v_mfma_f32_16x16x32_bf16 v[88:91], v[96:99], v[170:173], v[88:91]
	v_mfma_f32_16x16x32_bf16 v[24:27], v[104:107], v[170:173], v[24:27]
	v_mfma_f32_16x16x32_bf16 v[84:87], v[96:99], v[184:187], v[84:87]
	v_mfma_f32_16x16x32_bf16 v[20:23], v[104:107], v[184:187], v[20:23]
	v_mfma_f32_16x16x32_bf16 v[80:83], v[96:99], v[192:195], v[80:83]
	v_mfma_f32_16x16x32_bf16 v[16:19], v[104:107], v[192:195], v[16:19]
	v_mfma_f32_16x16x32_bf16 v[92:95], v[100:103], v[166:169], v[92:95]
	v_mfma_f32_16x16x32_bf16 v[28:31], v[158:161], v[166:169], v[28:31]
	v_mfma_f32_16x16x32_bf16 v[88:91], v[100:103], v[180:183], v[88:91]
	v_mfma_f32_16x16x32_bf16 v[24:27], v[158:161], v[180:183], v[24:27]
	v_mfma_f32_16x16x32_bf16 v[84:87], v[100:103], v[188:191], v[84:87]
	v_mfma_f32_16x16x32_bf16 v[20:23], v[158:161], v[188:191], v[20:23]
	v_mfma_f32_16x16x32_bf16 v[80:83], v[100:103], v[198:201], v[80:83]
	v_mfma_f32_16x16x32_bf16 v[16:19], v[158:161], v[198:201], v[16:19]
	s_barrier
	s_add_u32 s62, s66, 0x80080
	s_addc_u32 s63, s67, 0
	s_add_i32 s34, s35, s39
	s_mov_b32 m0, s34
	v_lshl_add_u64 v[96:97], s[62:63], 0, v[146:147]
	global_load_lds_dwordx4 v[96:97], off
	s_add_i32 m0, s34, 0x2000
	v_lshl_add_u64 v[96:97], s[62:63], 0, v[142:143]
	global_load_lds_dwordx4 v[96:97], off
	s_waitcnt vmcnt(6)
	s_barrier
	v_mfma_f32_16x16x32_bf16 v[76:79], v[208:211], v[162:165], v[76:79]
	v_mfma_f32_16x16x32_bf16 v[12:15], v[216:219], v[162:165], v[12:15]
	v_mfma_f32_16x16x32_bf16 v[68:71], v[208:211], v[170:173], v[68:71]
	v_mfma_f32_16x16x32_bf16 v[4:7], v[216:219], v[170:173], v[4:7]
	v_mfma_f32_16x16x32_bf16 v[72:75], v[208:211], v[184:187], v[72:75]
	v_mfma_f32_16x16x32_bf16 v[8:11], v[216:219], v[184:187], v[8:11]
	v_mfma_f32_16x16x32_bf16 v[64:67], v[208:211], v[192:195], v[64:67]
	v_mfma_f32_16x16x32_bf16 v[0:3], v[216:219], v[192:195], v[0:3]
	v_mfma_f32_16x16x32_bf16 v[76:79], v[212:215], v[166:169], v[76:79]
	v_mfma_f32_16x16x32_bf16 v[12:15], v[220:223], v[166:169], v[12:15]
	v_mfma_f32_16x16x32_bf16 v[68:71], v[212:215], v[180:183], v[68:71]
	v_mfma_f32_16x16x32_bf16 v[4:7], v[220:223], v[180:183], v[4:7]
	v_mfma_f32_16x16x32_bf16 v[72:75], v[212:215], v[188:191], v[72:75]
	v_mfma_f32_16x16x32_bf16 v[8:11], v[220:223], v[188:191], v[8:11]
	v_mfma_f32_16x16x32_bf16 v[64:67], v[212:215], v[198:201], v[64:67]
	v_mfma_f32_16x16x32_bf16 v[0:3], v[220:223], v[198:201], v[0:3]
	s_add_i32 s83, s83, 2
	s_add_u32 s81, s81, 0x100
	s_addc_u32 s82, s82, 0
	s_cmp_gt_u32 s83, 29
	s_mov_b64 s[62:63], s[64:65]
	s_barrier
	s_cbranch_scc0 .LBB0_173
	v_lshl_or_b32 v158, s70, 7, v150
	v_ashrrev_i32_e32 v159, 31, v158
	v_lshlrev_b64 v[96:97], 2, v[158:159]
	v_lshl_add_u64 v[98:99], s[30:31], 0, v[96:97]
	v_lshl_add_u64 v[100:101], s[46:47], 0, v[96:97]
	v_lshl_add_u64 v[102:103], s[24:25], 0, v[96:97]
	global_load_dwordx4 v[160:163], v[98:99], off
	global_load_dwordx4 v[170:173], v[100:101], off
	v_lshl_add_u64 v[98:99], s[42:43], 0, v[96:97]
	v_lshl_add_u64 v[100:101], s[48:49], 0, v[96:97]
	global_load_dwordx4 v[104:107], v[102:103], off
	global_load_dwordx4 v[164:167], v[98:99], off
	global_load_dwordx4 v[208:211], v[100:101], off
	v_lshl_add_u64 v[100:101], s[50:51], 0, v[96:97]
	global_load_dwordx4 v[212:215], v[100:101], off
	v_lshl_add_u64 v[98:99], s[26:27], 0, v[96:97]
	global_load_dwordx4 v[198:201], v[98:99], off
	v_lshl_add_u64 v[96:97], s[52:53], 0, v[96:97]
	global_load_dwordx4 v[216:219], v[96:97], off
	v_mov_b32_e32 v96, v177
	v_mov_b32_e32 v97, v177
	s_mov_b32 s62, 0xbf317218
	v_mov_b32_dpp v96, v126 row_ror:1 row_mask:0xf bank_mask:0xf
	v_mov_b32_dpp v97, v127 row_ror:1 row_mask:0xf bank_mask:0xf
	s_mov_b32 s34, 0xbfb8aa3b
	v_mov_b32_e32 v100, v177
	v_mov_b32_e32 v101, v177
	v_mov_b32_e32 v224, v177
	v_mov_b32_e32 v225, v177
	v_mov_b32_dpp v100, v138 row_ror:15 row_mask:0xf bank_mask:0xf
	v_mov_b32_dpp v101, v139 row_ror:15 row_mask:0xf bank_mask:0xf
	v_mov_b32_e32 v220, v177
	v_mov_b32_e32 v221, v177
	v_mov_b32_dpp v224, v112 row_ror:1 row_mask:0xf bank_mask:0xf
	v_mov_b32_dpp v225, v113 row_ror:1 row_mask:0xf bank_mask:0xf
	v_mov_b32_dpp v220, v128 row_ror:1 row_mask:0xf bank_mask:0xf
	v_mov_b32_dpp v221, v129 row_ror:1 row_mask:0xf bank_mask:0xf
	v_mov_b32_e32 v222, v177
	v_mov_b32_e32 v223, v177
	v_mov_b32_e32 v108, v177
	v_mov_b32_e32 v180, v177
	v_mov_b32_e32 v109, v177
	v_mov_b32_e32 v181, v177
	v_mov_b32_dpp v222, v140 row_ror:15 row_mask:0xf bank_mask:0xf
	v_mov_b32_dpp v223, v141 row_ror:15 row_mask:0xf bank_mask:0xf
	v_mov_b32_dpp v108, v110 row_ror:1 row_mask:0xf bank_mask:0xf
	v_mov_b32_dpp v180, v122 row_ror:15 row_mask:0xf bank_mask:0xf
	v_mov_b32_dpp v109, v111 row_ror:1 row_mask:0xf bank_mask:0xf
	v_mov_b32_dpp v181, v123 row_ror:15 row_mask:0xf bank_mask:0xf
	v_mov_b32_e32 v226, v177
	v_mov_b32_e32 v227, v177
	v_cmp_gt_i32_e32 vcc, 15, v151
	v_mov_b32_dpp v226, v124 row_ror:15 row_mask:0xf bank_mask:0xf
	v_mov_b32_dpp v227, v125 row_ror:15 row_mask:0xf bank_mask:0xf
	s_mov_b64 s[68:69], -1
	s_waitcnt vmcnt(0)
	v_pk_mul_f32 v[192:193], v[160:161], s[62:63] op_sel_hi:[1,0]
	v_pk_mul_f32 v[168:169], v[172:173], s[34:35] op_sel_hi:[1,0]
	v_pk_mul_f32 v[228:229], v[126:127], v[192:193]
	v_pk_mul_f32 v[194:195], v[162:163], s[62:63] op_sel_hi:[1,0]
	v_pk_mul_f32 v[186:187], v[104:105], s[62:63] op_sel_hi:[1,0]
	v_pk_mul_f32 v[188:189], v[166:167], s[62:63] op_sel_hi:[1,0]
	v_pk_mul_f32 v[172:173], v[210:211], s[34:35] op_sel_hi:[1,0]
	v_pk_mul_f32 v[96:97], v[186:187], v[96:97]
	v_pk_mul_f32 v[166:167], v[214:215], s[34:35] op_sel_hi:[1,0]
	v_pk_mul_f32 v[210:211], v[134:135], v[192:193]
	v_pk_mul_f32 v[214:215], v[130:131], v[192:193]
	v_pk_mul_f32 v[182:183], v[164:165], s[62:63] op_sel_hi:[1,0]
	v_pk_fma_f32 v[96:97], v[138:139], v[192:193], v[96:97]
	v_pk_fma_f32 v[210:211], v[138:139], v[186:187], v[210:211]
	v_pk_fma_f32 v[214:215], v[134:135], v[186:187], v[214:215]
	v_pk_fma_f32 v[228:229], v[130:131], v[186:187], v[228:229]
	v_pk_fma_f32 v[96:97], v[134:135], v[182:183], v[96:97]
	v_pk_fma_f32 v[210:211], v[130:131], v[182:183], v[210:211]
	v_pk_fma_f32 v[214:215], v[126:127], v[182:183], v[214:215]
	v_pk_fma_f32 v[100:101], v[182:183], v[100:101], v[228:229]
	v_pk_mul_f32 v[190:191], v[106:107], s[62:63] op_sel_hi:[1,0]
	v_pk_mul_f32 v[174:175], v[198:199], s[62:63] op_sel_hi:[1,0]
	v_pk_fma_f32 v[96:97], v[198:199], s[62:63], v[96:97] op_sel_hi:[1,0,1]
	v_pk_fma_f32 v[210:211], v[198:199], s[62:63], v[210:211] op_sel_hi:[1,0,1]
	v_pk_fma_f32 v[214:215], v[198:199], s[62:63], v[214:215] op_sel_hi:[1,0,1]
	v_pk_fma_f32 v[100:101], v[198:199], s[62:63], v[100:101] op_sel_hi:[1,0,1]
	v_pk_mul_f32 v[198:199], v[168:169], v[224:225]
	v_pk_mul_f32 v[164:165], v[170:171], s[34:35] op_sel_hi:[1,0]
	v_pk_mul_f32 v[170:171], v[208:209], s[34:35] op_sel_hi:[1,0]
	v_pk_mul_f32 v[162:163], v[212:213], s[34:35] op_sel_hi:[1,0]
	v_pk_mul_f32 v[104:105], v[190:191], v[220:221]
	v_pk_mul_f32 v[208:209], v[136:137], v[194:195]
	v_pk_mul_f32 v[212:213], v[132:133], v[194:195]
	v_pk_mul_f32 v[220:221], v[128:129], v[194:195]
	v_pk_fma_f32 v[198:199], v[124:125], v[172:173], v[198:199]
	v_pk_fma_f32 v[104:105], v[140:141], v[194:195], v[104:105]
	v_pk_fma_f32 v[208:209], v[140:141], v[190:191], v[208:209]
	v_pk_fma_f32 v[212:213], v[136:137], v[190:191], v[212:213]
	v_pk_fma_f32 v[220:221], v[132:133], v[190:191], v[220:221]
	v_pk_fma_f32 v[198:199], v[116:117], v[166:167], v[198:199]
	v_pk_mul_f32 v[232:233], v[110:111], v[170:171]
	v_pk_fma_f32 v[104:105], v[136:137], v[188:189], v[104:105]
	v_pk_fma_f32 v[208:209], v[132:133], v[188:189], v[208:209]
	v_pk_fma_f32 v[212:213], v[128:129], v[188:189], v[212:213]
	v_pk_fma_f32 v[220:221], v[188:189], v[222:223], v[220:221]
	v_pk_fma_f32 v[198:199], v[218:219], s[34:35], v[198:199] op_sel_hi:[1,0,1]
	v_pk_fma_f32 v[232:233], v[118:119], v[164:165], v[232:233]
	v_pk_mul_f32 v[184:185], v[200:201], s[62:63] op_sel_hi:[1,0]
	v_pk_fma_f32 v[104:105], v[200:201], s[62:63], v[104:105] op_sel_hi:[1,0,1]
	v_pk_fma_f32 v[208:209], v[200:201], s[62:63], v[208:209] op_sel_hi:[1,0,1]
	v_pk_fma_f32 v[212:213], v[200:201], s[62:63], v[212:213] op_sel_hi:[1,0,1]
	v_pk_fma_f32 v[200:201], v[200:201], s[62:63], v[220:221] op_sel_hi:[1,0,1]
	v_pk_mul_f32 v[108:109], v[164:165], v[108:109]
	v_pk_mul_f32 v[220:221], v[116:117], v[172:173]
	v_pk_mul_f32 v[222:223], v[114:115], v[170:171]
	v_pk_fma_f32 v[180:181], v[162:163], v[180:181], v[232:233]
	v_exp_f32_e32 v232, v198
	v_exp_f32_e32 v233, v199
	v_pk_fma_f32 v[108:109], v[122:123], v[170:171], v[108:109]
	v_pk_fma_f32 v[220:221], v[124:125], v[168:169], v[220:221]
	v_pk_fma_f32 v[222:223], v[122:123], v[164:165], v[222:223]
	v_pk_mul_f32 v[228:229], v[118:119], v[170:171]
	v_pk_fma_f32 v[108:109], v[114:115], v[162:163], v[108:109]
	v_pk_fma_f32 v[220:221], v[120:121], v[166:167], v[220:221]
	v_pk_fma_f32 v[222:223], v[118:119], v[162:163], v[222:223]
	v_pk_fma_f32 v[228:229], v[114:115], v[164:165], v[228:229]
	v_pk_mul_f32 v[230:231], v[112:113], v[172:173]
	v_pk_fma_f32 v[108:109], v[216:217], s[34:35], v[108:109] op_sel_hi:[1,0,1]
	v_pk_fma_f32 v[220:221], v[218:219], s[34:35], v[220:221] op_sel_hi:[1,0,1]
	v_pk_fma_f32 v[222:223], v[216:217], s[34:35], v[222:223] op_sel_hi:[1,0,1]
	v_pk_fma_f32 v[228:229], v[110:111], v[162:163], v[228:229]
	v_pk_fma_f32 v[230:231], v[120:121], v[168:169], v[230:231]
	v_pk_mul_f32 v[106:107], v[216:217], s[34:35] op_sel_hi:[1,0]
	v_pk_fma_f32 v[228:229], v[216:217], s[34:35], v[228:229] op_sel_hi:[1,0,1]
	v_pk_fma_f32 v[226:227], v[166:167], v[226:227], v[230:231]
	v_exp_f32_e32 v230, v108
	v_exp_f32_e32 v231, v109
	v_pk_fma_f32 v[180:181], v[216:217], s[34:35], v[180:181] op_sel_hi:[1,0,1]
	v_pk_add_f32 v[216:217], v[232:233], 1.0 op_sel_hi:[1,0]
	v_pk_mul_f32 v[104:105], v[104:105], v[198:199]
	v_pk_mul_f32 v[96:97], v[96:97], v[108:109]
	v_exp_f32_e32 v108, v222
	v_exp_f32_e32 v198, v220
	v_exp_f32_e32 v199, v221
	v_exp_f32_e32 v109, v223
	v_pk_mul_f32 v[224:225], v[120:121], v[172:173]
	v_rcp_f32_e32 v216, v216
	v_rcp_f32_e32 v217, v217
	v_pk_fma_f32 v[224:225], v[116:117], v[168:169], v[224:225]
	v_pk_add_f32 v[198:199], v[198:199], 1.0 op_sel_hi:[1,0]
	v_pk_fma_f32 v[224:225], v[112:113], v[166:167], v[224:225]
	v_pk_add_f32 v[108:109], v[108:109], 1.0 op_sel_hi:[1,0]
	v_pk_fma_f32 v[224:225], v[218:219], s[34:35], v[224:225] op_sel_hi:[1,0,1]
	v_pk_mul_f32 v[104:105], v[104:105], v[216:217]
	v_rcp_f32_e32 v108, v108
	v_rcp_f32_e32 v109, v109
	v_rcp_f32_e32 v198, v198
	v_rcp_f32_e32 v199, v199
	v_pk_mul_f32 v[208:209], v[208:209], v[220:221]
	v_exp_f32_e32 v216, v228
	v_exp_f32_e32 v220, v224
	v_exp_f32_e32 v221, v225
	v_exp_f32_e32 v217, v229
	v_pk_mul_f32 v[210:211], v[210:211], v[222:223]
	v_pk_mul_f32 v[160:161], v[218:219], s[34:35] op_sel_hi:[1,0]
	v_pk_fma_f32 v[218:219], v[218:219], s[34:35], v[226:227] op_sel_hi:[1,0,1]
	v_pk_mul_f32 v[198:199], v[208:209], v[198:199]
	v_pk_mul_f32 v[208:209], v[210:211], v[108:109]
	v_pk_add_f32 v[108:109], v[220:221], 1.0 op_sel_hi:[1,0]
	v_pk_add_f32 v[210:211], v[216:217], 1.0 op_sel_hi:[1,0]
	v_rcp_f32_e32 v108, v108
	v_rcp_f32_e32 v210, v210
	v_rcp_f32_e32 v211, v211
	v_rcp_f32_e32 v109, v109
	v_exp_f32_e32 v216, v180
	v_exp_f32_e32 v220, v218
	v_exp_f32_e32 v221, v219
	v_exp_f32_e32 v217, v181
	v_pk_add_f32 v[226:227], v[230:231], 1.0 op_sel_hi:[1,0]
	v_pk_mul_f32 v[212:213], v[212:213], v[224:225]
	v_pk_mul_f32 v[214:215], v[214:215], v[228:229]
	v_rcp_f32_e32 v226, v226
	v_rcp_f32_e32 v227, v227
	v_pk_mul_f32 v[212:213], v[212:213], v[108:109]
	v_pk_mul_f32 v[210:211], v[214:215], v[210:211]
	v_pk_add_f32 v[108:109], v[220:221], 1.0 op_sel_hi:[1,0]
	v_pk_add_f32 v[214:215], v[216:217], 1.0 op_sel_hi:[1,0]
	v_rcp_f32_e32 v108, v108
	v_rcp_f32_e32 v214, v214
	v_rcp_f32_e32 v109, v109
	v_rcp_f32_e32 v215, v215
	v_pk_mul_f32 v[96:97], v[96:97], v[226:227]
	v_pk_mul_f32 v[200:201], v[200:201], v[218:219]
	v_pk_mul_f32 v[100:101], v[100:101], v[180:181]
	v_pk_mul_f32 v[180:181], v[200:201], v[108:109]
	v_pk_mul_f32 v[200:201], v[100:101], v[214:215]
	v_cvt_pk_bf16_f32 v108, v96, v97
	v_cvt_pk_bf16_f32 v109, v104, v105
	v_cvt_pk_bf16_f32 v104, v208, v209
	v_cvt_pk_bf16_f32 v105, v198, v199
	v_cvt_pk_bf16_f32 v100, v210, v211
	v_cvt_pk_bf16_f32 v101, v212, v213
	s_nop 0
	v_cvt_pk_bf16_f32 v96, v200, v201
	v_cvt_pk_bf16_f32 v97, v180, v181
	s_and_saveexec_b64 s[62:63], vcc
	v_cmp_eq_u32_e32 vcc, 0, v151
	s_orn2_b64 s[68:69], vcc, exec
	s_or_b64 exec, exec, s[62:63]
	s_lshl_b32 s34, s79, 2
	s_lshl_b32 s62, s70, 8
	s_add_i32 s64, s34, s38
	s_ashr_i32 s63, s62, 31
	v_lshlrev_b32_e32 v176, 2, v150
	s_mov_b64 s[66:67], exec
	s_and_b64 s[68:69], s[66:67], s[68:69]
	v_mov_b32_e32 v198, 0xbf1f24be
	s_mov_b64 exec, s[68:69]
	s_cbranch_execz .LBB0_178
	s_ashr_i32 s65, s64, 31
	s_lshl_b64 s[68:69], s[64:65], 2
	v_or_b32_e32 v178, s68, v152
	v_mov_b64_e32 v[180:181], s[4:5]
	s_mov_b32 s29, 0xb000
	v_mad_u64_u32 v[180:181], s[70:71], v178, s29, v[180:181]
	v_mad_i32_i24 v181, s69, v204, v181
	v_lshl_add_u64 v[180:181], s[62:63], 2, v[180:181]
	v_lshl_add_u64 v[180:181], v[180:181], 0, v[176:177]
	v_cndmask_b32_e64 v133, v133, v141, s[8:9]
	v_cndmask_b32_e64 v132, v132, v140, s[8:9]
	v_cndmask_b32_e64 v131, v131, v139, s[8:9]
	v_cndmask_b32_e64 v130, v130, v138, s[8:9]
	v_cndmask_b32_e64 v118, v118, v122, s[8:9]
	v_cndmask_b32_e64 v121, v121, v125, s[8:9]
	v_cndmask_b32_e64 v120, v120, v124, s[8:9]
	v_cndmask_b32_e64 v119, v119, v123, s[8:9]
	global_store_dwordx4 v[180:181], v[130:133], off
	global_store_dwordx4 v[180:181], v[118:121], off offset:512
	v_cndmask_b32_e64 v125, v129, v137, s[8:9]
	v_cndmask_b32_e64 v124, v128, v136, s[8:9]
	v_add_co_u32_e32 v118, vcc, s29, v180
	v_cndmask_b32_e64 v123, v127, v135, s[8:9]
	v_cndmask_b32_e64 v122, v126, v134, s[8:9]
	v_addc_co_u32_e32 v119, vcc, 0, v181, vcc
	v_cndmask_b32_e64 v113, v113, v117, s[8:9]
	v_cndmask_b32_e64 v112, v112, v116, s[8:9]
	v_cndmask_b32_e64 v111, v111, v115, s[8:9]
	v_cndmask_b32_e64 v110, v110, v114, s[8:9]
	global_store_dwordx4 v[118:119], v[122:125], off
	global_store_dwordx4 v[118:119], v[110:113], off offset:512

.LBB0_264:
	s_add_i32 s61, s24, 2
	s_add_u32 s26, s8, 0x80
	s_addc_u32 s25, s9, 0
	s_add_i32 s29, 0, 0x10000
	v_add_u32_e32 v140, s29, v193
	ds_read_b128 v[128:131], v140
	ds_read_b128 v[132:135], v140 offset:1024
	ds_read_b128 v[136:139], v140 offset:2048
	ds_read_b128 v[140:143], v140 offset:3072
	s_cmp_eq_u32 s47, s24
	s_cselect_b32 s24, s20, s26
	s_cselect_b32 s25, s21, s25
	s_cselect_b32 s27, s11, s60
	s_cselect_b32 s26, s10, s59
	v_lshl_add_u64 v[180:181], s[8:9], 0, v[174:175]
	s_add_i32 m0, s33, 0xc000
	ds_read_b128 v[144:147], v195
	ds_read_b128 v[148:151], v195 offset:1024
	ds_read_b128 v[152:155], v195 offset:2048
	ds_read_b128 v[156:159], v195 offset:3072
	ds_read_b128 v[160:163], v195 offset:4096
	ds_read_b128 v[164:167], v195 offset:5120
	ds_read_b128 v[184:187], v195 offset:6144
	ds_read_b128 v[188:191], v195 offset:7168
	global_load_lds_dwordx4 v[180:181], off
	s_add_i32 m0, s33, 0xe000
	v_lshl_add_u64 v[180:181], s[8:9], 0, v[182:183]
	global_load_lds_dwordx4 v[180:181], off
	s_waitcnt lgkmcnt(8)
	s_barrier
	s_waitcnt lgkmcnt(0)
	v_mfma_f32_16x16x32_bf16 v[124:127], v[128:131], v[144:147], v[124:127]
	v_mfma_f32_16x16x32_bf16 v[120:123], v[136:139], v[144:147], v[120:123]
	v_mfma_f32_16x16x32_bf16 v[108:111], v[128:131], v[152:155], v[108:111]
	v_mfma_f32_16x16x32_bf16 v[104:107], v[136:139], v[152:155], v[104:107]
	v_mfma_f32_16x16x32_bf16 v[92:95], v[128:131], v[160:163], v[92:95]
	v_mfma_f32_16x16x32_bf16 v[88:91], v[136:139], v[160:163], v[88:91]
	v_mfma_f32_16x16x32_bf16 v[76:79], v[128:131], v[184:187], v[76:79]
	v_mfma_f32_16x16x32_bf16 v[72:75], v[136:139], v[184:187], v[72:75]
	v_mfma_f32_16x16x32_bf16 v[124:127], v[132:135], v[148:151], v[124:127]
	v_mfma_f32_16x16x32_bf16 v[120:123], v[140:143], v[148:151], v[120:123]
	v_mfma_f32_16x16x32_bf16 v[108:111], v[132:135], v[156:159], v[108:111]
	v_mfma_f32_16x16x32_bf16 v[104:107], v[140:143], v[156:159], v[104:107]
	v_mfma_f32_16x16x32_bf16 v[92:95], v[132:135], v[164:167], v[92:95]
	v_mfma_f32_16x16x32_bf16 v[88:91], v[140:143], v[164:167], v[88:91]
	v_mfma_f32_16x16x32_bf16 v[76:79], v[132:135], v[188:191], v[76:79]
	v_mfma_f32_16x16x32_bf16 v[72:75], v[140:143], v[188:191], v[72:75]
	s_barrier
	s_add_i32 s34, 0, 0x14000
	s_add_i32 s29, s29, s31
	v_add_u32_e32 v178, s34, v193
	v_lshl_add_u64 v[180:181], s[26:27], 0, v[176:177]
	s_mov_b32 m0, s29
	ds_read_b128 v[196:199], v178
	ds_read_b128 v[208:211], v178 offset:1024
	ds_read_b128 v[212:215], v178 offset:2048
	ds_read_b128 v[216:219], v178 offset:3072
	global_load_lds_dwordx4 v[180:181], off
	s_add_i32 m0, s29, 0x2000
	v_lshl_add_u64 v[200:201], s[26:27], 0, v[168:169]
	global_load_lds_dwordx4 v[200:201], off
	s_barrier
	s_waitcnt lgkmcnt(0)
	v_mfma_f32_16x16x32_bf16 v[116:119], v[196:199], v[144:147], v[116:119]
	v_mfma_f32_16x16x32_bf16 v[112:115], v[212:215], v[144:147], v[112:115]
	v_mfma_f32_16x16x32_bf16 v[100:103], v[196:199], v[152:155], v[100:103]
	v_mfma_f32_16x16x32_bf16 v[96:99], v[212:215], v[152:155], v[96:99]
	v_mfma_f32_16x16x32_bf16 v[84:87], v[196:199], v[160:163], v[84:87]
	v_mfma_f32_16x16x32_bf16 v[80:83], v[212:215], v[160:163], v[80:83]
	v_mfma_f32_16x16x32_bf16 v[68:71], v[196:199], v[184:187], v[68:71]
	v_mfma_f32_16x16x32_bf16 v[64:67], v[212:215], v[184:187], v[64:67]
	v_mfma_f32_16x16x32_bf16 v[116:119], v[208:211], v[148:151], v[116:119]
	v_mfma_f32_16x16x32_bf16 v[112:115], v[216:219], v[148:151], v[112:115]
	v_mfma_f32_16x16x32_bf16 v[100:103], v[208:211], v[156:159], v[100:103]
	v_mfma_f32_16x16x32_bf16 v[96:99], v[216:219], v[156:159], v[96:99]
	v_mfma_f32_16x16x32_bf16 v[84:87], v[208:211], v[164:167], v[84:87]
	v_mfma_f32_16x16x32_bf16 v[80:83], v[216:219], v[164:167], v[80:83]
	v_mfma_f32_16x16x32_bf16 v[68:71], v[208:211], v[188:191], v[68:71]
	v_mfma_f32_16x16x32_bf16 v[64:67], v[216:219], v[188:191], v[64:67]
	s_mov_b32 m0, s33
	v_lshl_add_u64 v[220:221], s[24:25], 0, v[172:173]
	s_barrier
	ds_read_b128 v[144:147], v195 offset:16384
	ds_read_b128 v[148:151], v195 offset:17408
	ds_read_b128 v[152:155], v195 offset:18432
	ds_read_b128 v[156:159], v195 offset:19456
	ds_read_b128 v[160:163], v195 offset:20480
	ds_read_b128 v[164:167], v195 offset:21504
	ds_read_b128 v[184:187], v195 offset:22528
	ds_read_b128 v[188:191], v195 offset:23552
	global_load_lds_dwordx4 v[220:221], off
	s_mov_b32 m0, s37
	v_lshl_add_u64 v[222:223], s[24:25], 0, v[170:171]
	global_load_lds_dwordx4 v[222:223], off
	s_barrier
	s_waitcnt lgkmcnt(0)
	v_mfma_f32_16x16x32_bf16 v[60:63], v[128:131], v[144:147], v[60:63]
	v_mfma_f32_16x16x32_bf16 v[56:59], v[136:139], v[144:147], v[56:59]
	v_mfma_f32_16x16x32_bf16 v[44:47], v[128:131], v[152:155], v[44:47]
	v_mfma_f32_16x16x32_bf16 v[40:43], v[136:139], v[152:155], v[40:43]
	v_mfma_f32_16x16x32_bf16 v[28:31], v[128:131], v[160:163], v[28:31]
	v_mfma_f32_16x16x32_bf16 v[24:27], v[136:139], v[160:163], v[24:27]
	v_mfma_f32_16x16x32_bf16 v[12:15], v[128:131], v[184:187], v[12:15]
	v_mfma_f32_16x16x32_bf16 v[8:11], v[136:139], v[184:187], v[8:11]
	v_mfma_f32_16x16x32_bf16 v[60:63], v[132:135], v[148:151], v[60:63]
	v_mfma_f32_16x16x32_bf16 v[56:59], v[140:143], v[148:151], v[56:59]
	v_mfma_f32_16x16x32_bf16 v[44:47], v[132:135], v[156:159], v[44:47]
	v_mfma_f32_16x16x32_bf16 v[40:43], v[140:143], v[156:159], v[40:43]
	v_mfma_f32_16x16x32_bf16 v[28:31], v[132:135], v[164:167], v[28:31]
	v_mfma_f32_16x16x32_bf16 v[24:27], v[140:143], v[164:167], v[24:27]
	v_mfma_f32_16x16x32_bf16 v[12:15], v[132:135], v[188:191], v[12:15]
	v_mfma_f32_16x16x32_bf16 v[8:11], v[140:143], v[188:191], v[8:11]
	s_barrier
	s_add_u32 s26, s26, s44
	s_addc_u32 s27, s27, 0
	s_add_i32 s29, s34, s31
	v_lshl_add_u64 v[224:225], s[26:27], 0, v[176:177]
	s_mov_b32 m0, s29
	v_lshl_add_u64 v[226:227], s[26:27], 0, v[168:169]
	global_load_lds_dwordx4 v[224:225], off
	s_add_i32 m0, s29, 0x2000
	s_nop 0
	global_load_lds_dwordx4 v[226:227], off
	s_waitcnt vmcnt(6)
	s_barrier
	v_mfma_f32_16x16x32_bf16 v[52:55], v[196:199], v[144:147], v[52:55]
	v_mfma_f32_16x16x32_bf16 v[48:51], v[212:215], v[144:147], v[48:51]
	v_mfma_f32_16x16x32_bf16 v[36:39], v[196:199], v[152:155], v[36:39]
	v_mfma_f32_16x16x32_bf16 v[32:35], v[212:215], v[152:155], v[32:35]
	v_mfma_f32_16x16x32_bf16 v[20:23], v[196:199], v[160:163], v[20:23]
	v_mfma_f32_16x16x32_bf16 v[16:19], v[212:215], v[160:163], v[16:19]
	v_mfma_f32_16x16x32_bf16 v[4:7], v[196:199], v[184:187], v[4:7]
	v_mfma_f32_16x16x32_bf16 v[0:3], v[212:215], v[184:187], v[0:3]
	v_mfma_f32_16x16x32_bf16 v[52:55], v[208:211], v[148:151], v[52:55]
	v_mfma_f32_16x16x32_bf16 v[48:51], v[216:219], v[148:151], v[48:51]
	v_mfma_f32_16x16x32_bf16 v[36:39], v[208:211], v[156:159], v[36:39]
	v_mfma_f32_16x16x32_bf16 v[32:35], v[216:219], v[156:159], v[32:35]
	v_mfma_f32_16x16x32_bf16 v[20:23], v[208:211], v[164:167], v[20:23]
	v_mfma_f32_16x16x32_bf16 v[16:19], v[216:219], v[164:167], v[16:19]
	v_mfma_f32_16x16x32_bf16 v[4:7], v[208:211], v[188:191], v[4:7]
	v_mfma_f32_16x16x32_bf16 v[0:3], v[216:219], v[188:191], v[0:3]
	s_add_i32 s26, 0, 0x18000
	v_add_u32_e32 v140, s26, v193
	s_barrier
	ds_read_b128 v[128:131], v140
	ds_read_b128 v[132:135], v140 offset:1024
	ds_read_b128 v[136:139], v140 offset:2048
	ds_read_b128 v[140:143], v140 offset:3072
	s_add_u32 s24, s24, s44
	s_addc_u32 s25, s25, 0
	s_mov_b32 m0, s38
	v_lshl_add_u64 v[196:197], s[24:25], 0, v[172:173]
	ds_read_b128 v[144:147], v195 offset:32768
	ds_read_b128 v[148:151], v195 offset:33792
	ds_read_b128 v[152:155], v195 offset:34816
	ds_read_b128 v[156:159], v195 offset:35840
	ds_read_b128 v[160:163], v195 offset:36864
	ds_read_b128 v[164:167], v195 offset:37888
	ds_read_b128 v[184:187], v195 offset:38912
	ds_read_b128 v[188:191], v195 offset:39936
	global_load_lds_dwordx4 v[196:197], off
	s_mov_b32 m0, s39
	v_lshl_add_u64 v[196:197], s[24:25], 0, v[170:171]
	global_load_lds_dwordx4 v[196:197], off
	s_waitcnt lgkmcnt(8)
	s_barrier
	s_waitcnt lgkmcnt(0)
	v_mfma_f32_16x16x32_bf16 v[124:127], v[128:131], v[144:147], v[124:127]
	v_mfma_f32_16x16x32_bf16 v[120:123], v[136:139], v[144:147], v[120:123]
	v_mfma_f32_16x16x32_bf16 v[108:111], v[128:131], v[152:155], v[108:111]
	v_mfma_f32_16x16x32_bf16 v[104:107], v[136:139], v[152:155], v[104:107]
	v_mfma_f32_16x16x32_bf16 v[92:95], v[128:131], v[160:163], v[92:95]
	v_mfma_f32_16x16x32_bf16 v[88:91], v[136:139], v[160:163], v[88:91]
	v_mfma_f32_16x16x32_bf16 v[76:79], v[128:131], v[184:187], v[76:79]
	v_mfma_f32_16x16x32_bf16 v[72:75], v[136:139], v[184:187], v[72:75]
	v_mfma_f32_16x16x32_bf16 v[124:127], v[132:135], v[148:151], v[124:127]
	v_mfma_f32_16x16x32_bf16 v[120:123], v[140:143], v[148:151], v[120:123]
	v_mfma_f32_16x16x32_bf16 v[108:111], v[132:135], v[156:159], v[108:111]
	v_mfma_f32_16x16x32_bf16 v[104:107], v[140:143], v[156:159], v[104:107]
	v_mfma_f32_16x16x32_bf16 v[92:95], v[132:135], v[164:167], v[92:95]
	v_mfma_f32_16x16x32_bf16 v[88:91], v[140:143], v[164:167], v[88:91]
	v_mfma_f32_16x16x32_bf16 v[76:79], v[132:135], v[188:191], v[76:79]
	v_mfma_f32_16x16x32_bf16 v[72:75], v[140:143], v[188:191], v[72:75]
	s_barrier
	s_add_i32 s24, 0, 0x1c000
	s_add_i32 s25, s26, s31
	v_add_u32_e32 v178, s24, v193
	v_lshl_add_u64 v[180:181], v[180:181], 0, s[40:41]
	s_mov_b32 m0, s25
	ds_read_b128 v[196:199], v178
	ds_read_b128 v[208:211], v178 offset:1024
	ds_read_b128 v[212:215], v178 offset:2048
	ds_read_b128 v[216:219], v178 offset:3072
	global_load_lds_dwordx4 v[180:181], off
	s_add_i32 m0, s25, 0x2000
	v_lshl_add_u64 v[180:181], v[200:201], 0, s[40:41]
	global_load_lds_dwordx4 v[180:181], off
	s_barrier
	s_waitcnt lgkmcnt(0)
	v_mfma_f32_16x16x32_bf16 v[116:119], v[196:199], v[144:147], v[116:119]
	v_mfma_f32_16x16x32_bf16 v[112:115], v[212:215], v[144:147], v[112:115]
	v_mfma_f32_16x16x32_bf16 v[100:103], v[196:199], v[152:155], v[100:103]
	v_mfma_f32_16x16x32_bf16 v[96:99], v[212:215], v[152:155], v[96:99]
	v_mfma_f32_16x16x32_bf16 v[84:87], v[196:199], v[160:163], v[84:87]
	v_mfma_f32_16x16x32_bf16 v[80:83], v[212:215], v[160:163], v[80:83]
	v_mfma_f32_16x16x32_bf16 v[68:71], v[196:199], v[184:187], v[68:71]
	v_mfma_f32_16x16x32_bf16 v[64:67], v[212:215], v[184:187], v[64:67]
	v_mfma_f32_16x16x32_bf16 v[116:119], v[208:211], v[148:151], v[116:119]
	v_mfma_f32_16x16x32_bf16 v[112:115], v[216:219], v[148:151], v[112:115]
	v_mfma_f32_16x16x32_bf16 v[100:103], v[208:211], v[156:159], v[100:103]
	v_mfma_f32_16x16x32_bf16 v[96:99], v[216:219], v[156:159], v[96:99]
	v_mfma_f32_16x16x32_bf16 v[84:87], v[208:211], v[164:167], v[84:87]
	v_mfma_f32_16x16x32_bf16 v[80:83], v[216:219], v[164:167], v[80:83]
	v_mfma_f32_16x16x32_bf16 v[68:71], v[208:211], v[188:191], v[68:71]
	v_mfma_f32_16x16x32_bf16 v[64:67], v[216:219], v[188:191], v[64:67]
	s_mov_b32 m0, s43
	v_lshl_add_u64 v[180:181], v[220:221], 0, s[40:41]
	s_barrier
	ds_read_b128 v[144:147], v195 offset:49152
	ds_read_b128 v[148:151], v195 offset:50176
	ds_read_b128 v[152:155], v195 offset:51200
	ds_read_b128 v[156:159], v195 offset:52224
	ds_read_b128 v[160:163], v195 offset:53248
	ds_read_b128 v[164:167], v195 offset:54272
	ds_read_b128 v[184:187], v195 offset:55296
	ds_read_b128 v[188:191], v195 offset:56320
	global_load_lds_dwordx4 v[180:181], off
	s_mov_b32 m0, s46
	v_lshl_add_u64 v[180:181], v[222:223], 0, s[40:41]
	global_load_lds_dwordx4 v[180:181], off
	s_barrier
	s_waitcnt lgkmcnt(0)
	v_mfma_f32_16x16x32_bf16 v[60:63], v[128:131], v[144:147], v[60:63]
	v_mfma_f32_16x16x32_bf16 v[56:59], v[136:139], v[144:147], v[56:59]
	v_mfma_f32_16x16x32_bf16 v[44:47], v[128:131], v[152:155], v[44:47]
	v_mfma_f32_16x16x32_bf16 v[40:43], v[136:139], v[152:155], v[40:43]
	v_mfma_f32_16x16x32_bf16 v[28:31], v[128:131], v[160:163], v[28:31]
	v_mfma_f32_16x16x32_bf16 v[24:27], v[136:139], v[160:163], v[24:27]
	v_mfma_f32_16x16x32_bf16 v[12:15], v[128:131], v[184:187], v[12:15]
	v_mfma_f32_16x16x32_bf16 v[8:11], v[136:139], v[184:187], v[8:11]
	v_mfma_f32_16x16x32_bf16 v[60:63], v[132:135], v[148:151], v[60:63]
	v_mfma_f32_16x16x32_bf16 v[56:59], v[140:143], v[148:151], v[56:59]
	v_mfma_f32_16x16x32_bf16 v[44:47], v[132:135], v[156:159], v[44:47]
	v_mfma_f32_16x16x32_bf16 v[40:43], v[140:143], v[156:159], v[40:43]
	v_mfma_f32_16x16x32_bf16 v[28:31], v[132:135], v[164:167], v[28:31]
	v_mfma_f32_16x16x32_bf16 v[24:27], v[140:143], v[164:167], v[24:27]
	v_mfma_f32_16x16x32_bf16 v[12:15], v[132:135], v[188:191], v[12:15]
	v_mfma_f32_16x16x32_bf16 v[8:11], v[140:143], v[188:191], v[8:11]
	s_barrier
	s_add_i32 s24, s24, s31
	s_mov_b32 m0, s24
	v_lshl_add_u64 v[128:129], v[224:225], 0, s[40:41]
	global_load_lds_dwordx4 v[128:129], off
	s_add_i32 m0, s24, 0x2000
	v_lshl_add_u64 v[128:129], v[226:227], 0, s[40:41]
	global_load_lds_dwordx4 v[128:129], off
	s_waitcnt vmcnt(6)
	s_barrier
	v_mfma_f32_16x16x32_bf16 v[52:55], v[196:199], v[144:147], v[52:55]
	v_mfma_f32_16x16x32_bf16 v[48:51], v[212:215], v[144:147], v[48:51]
	v_mfma_f32_16x16x32_bf16 v[36:39], v[196:199], v[152:155], v[36:39]
	v_mfma_f32_16x16x32_bf16 v[32:35], v[212:215], v[152:155], v[32:35]
	v_mfma_f32_16x16x32_bf16 v[20:23], v[196:199], v[160:163], v[20:23]
	v_mfma_f32_16x16x32_bf16 v[16:19], v[212:215], v[160:163], v[16:19]
	v_mfma_f32_16x16x32_bf16 v[4:7], v[196:199], v[184:187], v[4:7]
	v_mfma_f32_16x16x32_bf16 v[0:3], v[212:215], v[184:187], v[0:3]
	v_mfma_f32_16x16x32_bf16 v[52:55], v[208:211], v[148:151], v[52:55]
	v_mfma_f32_16x16x32_bf16 v[48:51], v[216:219], v[148:151], v[48:51]
	v_mfma_f32_16x16x32_bf16 v[36:39], v[208:211], v[156:159], v[36:39]
	v_mfma_f32_16x16x32_bf16 v[32:35], v[216:219], v[156:159], v[32:35]
	v_mfma_f32_16x16x32_bf16 v[20:23], v[208:211], v[164:167], v[20:23]
	v_mfma_f32_16x16x32_bf16 v[16:19], v[216:219], v[164:167], v[16:19]
	v_mfma_f32_16x16x32_bf16 v[4:7], v[208:211], v[188:191], v[4:7]
	v_mfma_f32_16x16x32_bf16 v[0:3], v[216:219], v[188:191], v[0:3]
	s_add_u32 s59, s59, 0x100
	s_addc_u32 s60, s60, 0
	s_add_u32 s8, s8, 0x100
	s_addc_u32 s9, s9, 0
	s_cmp_ge_u32 s61, s42
	s_mov_b32 s24, s61
	s_barrier
	s_cbranch_scc0 .LBB0_264
	s_sub_i32 s8, s57, 32
	s_lshr_b32 s8, s8, 3
	s_cmp_lt_i32 s57, 32
	s_cselect_b32 s26, 8, s8
	v_readlane_b32 s8, v255, 40
	v_readlane_b32 s9, v255, 41
	s_load_dwordx16 s[60:75], s[8:9], 0x0
	v_lshl_or_b32 v184, s58, 8, v194
	v_ashrrev_i32_e32 v185, 31, v184
	v_lshlrev_b64 v[128:129], 2, v[184:185]
	v_lshl_add_u32 v186, s57, 8, v192
	s_waitcnt lgkmcnt(0)
	s_cselect_b32 s24, s60, s50
	s_cselect_b32 s25, s61, s51
	s_add_i32 s8, s26, s53
	s_mul_hi_u32 s9, s8, 0xc000
	s_mul_i32 s8, s8, 0xc000
	s_add_u32 s8, s48, s8
	s_addc_u32 s9, s49, s9
	s_add_i32 s26, s54, s26
	s_mul_hi_u32 s27, s26, 0xc000
	s_mul_i32 s26, s26, 0xc000
	s_add_u32 s26, s48, s26
	s_addc_u32 s27, s49, s27
	v_lshl_add_u64 v[132:133], s[8:9], 0, v[128:129]
	v_lshl_add_u64 v[140:141], s[26:27], 0, v[128:129]
	global_load_dwordx4 v[144:147], v[132:133], off offset:16
	global_load_dwordx4 v[152:155], v[132:133], off
	global_load_dwordx4 v[148:151], v[140:141], off offset:16
	global_load_dwordx4 v[156:159], v[140:141], off
	global_load_dwordx4 v[128:131], v[132:133], off offset:528
	global_load_dwordx4 v[136:139], v[132:133], off offset:512
	s_nop 0
	global_load_dwordx4 v[132:135], v[140:141], off offset:528
	s_nop 0
	global_load_dwordx4 v[140:143], v[140:141], off offset:512
	v_lshl_add_u32 v196, v186, 11, v184
	v_lshlrev_b32_e32 v197, 2, v196
	v_lshlrev_b32_e32 v196, 1, v196
	s_and_b64 vcc, exec, s[4:5]
	s_cbranch_vccnz .Lres_f32
	global_load_dwordx4 v[164:167], v196, s[12:13]
	global_load_dwordx4 v[184:187], v196, s[12:13] offset:256
	s_add_u32 s62, s12, 0x10000
	s_addc_u32 s63, s13, 0
	global_load_dwordx4 v[188:191], v196, s[62:63]
	s_add_u32 s62, s12, 0x10000
	s_addc_u32 s63, s13, 0
	global_load_dwordx4 v[208:211], v196, s[62:63] offset:256
	s_add_u32 s62, s12, 0x20000
	s_addc_u32 s63, s13, 0
	global_load_dwordx4 v[212:215], v196, s[62:63]
	s_add_u32 s62, s12, 0x20000
	s_addc_u32 s63, s13, 0
	global_load_dwordx4 v[216:219], v196, s[62:63] offset:256
	s_add_u32 s62, s12, 0x30000
	s_addc_u32 s63, s13, 0
	global_load_dwordx4 v[220:223], v196, s[62:63]
	s_add_u32 s62, s12, 0x30000
	s_addc_u32 s63, s13, 0
	global_load_dwordx4 v[224:227], v196, s[62:63] offset:256
	s_waitcnt vmcnt(8)
	v_pk_add_f32 v[146:147], v[146:147], v[150:151]
	v_pk_add_f32 v[144:145], v[144:145], v[148:149]
	v_pk_add_f32 v[154:155], v[154:155], v[158:159]
	v_pk_add_f32 v[152:153], v[152:153], v[156:157]
	v_pk_add_f32 v[136:137], v[136:137], v[140:141]
	v_pk_add_f32 v[130:131], v[130:131], v[134:135]
	v_pk_add_f32 v[128:129], v[128:129], v[132:133]
	v_pk_add_f32 v[138:139], v[138:139], v[142:143]
	s_add_u32 s62, s12, 0x80000
	s_addc_u32 s63, s13, 0
	global_load_dwordx4 v[148:151], v196, s[62:63]
	s_add_u32 s62, s12, 0x80000
	s_addc_u32 s63, s13, 0
	global_load_dwordx4 v[156:159], v196, s[62:63] offset:256
	s_add_u32 s62, s12, 0x90000
	s_addc_u32 s63, s13, 0
	global_load_dwordx4 v[132:135], v196, s[62:63]
	s_add_u32 s62, s12, 0x90000
	s_addc_u32 s63, s13, 0
	global_load_dwordx4 v[140:143], v196, s[62:63] offset:256
	s_waitcnt vmcnt(11)
	v_lshlrev_b32_e32 v160, 16, v164
	v_and_b32_e32 v161, 0xffff0000, v164
	v_lshlrev_b32_e32 v162, 16, v165
	v_and_b32_e32 v163, 0xffff0000, v165
	v_lshlrev_b32_e32 v164, 16, v166
	v_and_b32_e32 v165, 0xffff0000, v166
	v_lshlrev_b32_e32 v166, 16, v167
	v_and_b32_e32 v167, 0xffff0000, v167
	v_pk_fma_f32 v[124:125], v[124:125], v[152:153], v[160:161]
	v_pk_fma_f32 v[126:127], v[126:127], v[154:155], v[162:163]
	v_pk_fma_f32 v[120:121], v[120:121], v[144:145], v[164:165]
	v_pk_fma_f32 v[122:123], v[122:123], v[146:147], v[166:167]
	s_add_u32 s62, s12, 0xa0000
	s_addc_u32 s63, s13, 0
	global_load_dwordx4 v[164:167], v196, s[62:63]
	v_cvt_pk_bf16_f32 v124, v124, v125
	v_cvt_pk_bf16_f32 v125, v126, v127
	v_cvt_pk_bf16_f32 v126, v120, v121
	v_cvt_pk_bf16_f32 v127, v122, v123
	global_store_dwordx4 v196, v[124:127], s[12:13]
	s_waitcnt vmcnt(12)
	v_lshlrev_b32_e32 v160, 16, v184
	v_and_b32_e32 v161, 0xffff0000, v184
	v_lshlrev_b32_e32 v162, 16, v185
	v_and_b32_e32 v163, 0xffff0000, v185
	v_lshlrev_b32_e32 v184, 16, v186
	v_and_b32_e32 v185, 0xffff0000, v186
	v_lshlrev_b32_e32 v186, 16, v187
	v_and_b32_e32 v187, 0xffff0000, v187
	v_pk_fma_f32 v[116:117], v[116:117], v[136:137], v[160:161]
	v_pk_fma_f32 v[118:119], v[118:119], v[138:139], v[162:163]
	v_pk_fma_f32 v[112:113], v[112:113], v[128:129], v[184:185]
	v_pk_fma_f32 v[114:115], v[114:115], v[130:131], v[186:187]
	s_add_u32 s62, s12, 0xa0000
	s_addc_u32 s63, s13, 0
	global_load_dwordx4 v[184:187], v196, s[62:63] offset:256
	v_cvt_pk_bf16_f32 v116, v116, v117
	v_cvt_pk_bf16_f32 v117, v118, v119
	v_cvt_pk_bf16_f32 v118, v112, v113
	v_cvt_pk_bf16_f32 v119, v114, v115
	global_store_dwordx4 v196, v[116:119], s[12:13] offset:256
	s_waitcnt vmcnt(13)
	v_lshlrev_b32_e32 v160, 16, v188
	v_and_b32_e32 v161, 0xffff0000, v188
	v_lshlrev_b32_e32 v162, 16, v189
	v_and_b32_e32 v163, 0xffff0000, v189
	v_lshlrev_b32_e32 v188, 16, v190
	v_and_b32_e32 v189, 0xffff0000, v190
	v_lshlrev_b32_e32 v190, 16, v191
	v_and_b32_e32 v191, 0xffff0000, v191
	v_pk_fma_f32 v[108:109], v[108:109], v[152:153], v[160:161]
	v_pk_fma_f32 v[110:111], v[110:111], v[154:155], v[162:163]
	v_pk_fma_f32 v[104:105], v[104:105], v[144:145], v[188:189]
	v_pk_fma_f32 v[106:107], v[106:107], v[146:147], v[190:191]
	s_add_u32 s62, s12, 0xb0000
	s_addc_u32 s63, s13, 0
	global_load_dwordx4 v[188:191], v196, s[62:63]
	v_cvt_pk_bf16_f32 v108, v108, v109
	v_cvt_pk_bf16_f32 v109, v110, v111
	v_cvt_pk_bf16_f32 v110, v104, v105
	v_cvt_pk_bf16_f32 v111, v106, v107
	s_add_u32 s64, s12, 0x10000
	s_addc_u32 s65, s13, 0
	global_store_dwordx4 v196, v[108:111], s[64:65]
	s_waitcnt vmcnt(14)
	v_lshlrev_b32_e32 v160, 16, v208
	v_and_b32_e32 v161, 0xffff0000, v208
	v_lshlrev_b32_e32 v162, 16, v209
	v_and_b32_e32 v163, 0xffff0000, v209
	v_lshlrev_b32_e32 v208, 16, v210
	v_and_b32_e32 v209, 0xffff0000, v210
	v_lshlrev_b32_e32 v210, 16, v211
	v_and_b32_e32 v211, 0xffff0000, v211
	v_pk_fma_f32 v[100:101], v[100:101], v[136:137], v[160:161]
	v_pk_fma_f32 v[102:103], v[102:103], v[138:139], v[162:163]
	v_pk_fma_f32 v[96:97], v[96:97], v[128:129], v[208:209]
	v_pk_fma_f32 v[98:99], v[98:99], v[130:131], v[210:211]
	s_add_u32 s62, s12, 0xb0000
	s_addc_u32 s63, s13, 0
	global_load_dwordx4 v[208:211], v196, s[62:63] offset:256
	v_cvt_pk_bf16_f32 v100, v100, v101
	v_cvt_pk_bf16_f32 v101, v102, v103
	v_cvt_pk_bf16_f32 v102, v96, v97
	v_cvt_pk_bf16_f32 v103, v98, v99
	s_add_u32 s64, s12, 0x10000
	s_addc_u32 s65, s13, 0
	global_store_dwordx4 v196, v[100:103], s[64:65] offset:256
	s_waitcnt vmcnt(15)
	v_lshlrev_b32_e32 v160, 16, v212
	v_and_b32_e32 v161, 0xffff0000, v212
	v_lshlrev_b32_e32 v162, 16, v213
	v_and_b32_e32 v163, 0xffff0000, v213
	v_lshlrev_b32_e32 v212, 16, v214
	v_and_b32_e32 v213, 0xffff0000, v214
	v_lshlrev_b32_e32 v214, 16, v215
	v_and_b32_e32 v215, 0xffff0000, v215
	v_pk_fma_f32 v[92:93], v[92:93], v[152:153], v[160:161]
	v_pk_fma_f32 v[94:95], v[94:95], v[154:155], v[162:163]
	v_pk_fma_f32 v[88:89], v[88:89], v[144:145], v[212:213]
	v_pk_fma_f32 v[90:91], v[90:91], v[146:147], v[214:215]
	v_cvt_pk_bf16_f32 v92, v92, v93
	v_cvt_pk_bf16_f32 v93, v94, v95
	v_cvt_pk_bf16_f32 v94, v88, v89
	v_cvt_pk_bf16_f32 v95, v90, v91
	s_add_u32 s64, s12, 0x20000
	s_addc_u32 s65, s13, 0
	global_store_dwordx4 v196, v[92:95], s[64:65]
	s_waitcnt vmcnt(15)
	v_lshlrev_b32_e32 v160, 16, v216
	v_and_b32_e32 v161, 0xffff0000, v216
	v_lshlrev_b32_e32 v162, 16, v217
	v_and_b32_e32 v163, 0xffff0000, v217
	v_lshlrev_b32_e32 v216, 16, v218
	v_and_b32_e32 v217, 0xffff0000, v218
	v_lshlrev_b32_e32 v218, 16, v219
	v_and_b32_e32 v219, 0xffff0000, v219
	v_pk_fma_f32 v[84:85], v[84:85], v[136:137], v[160:161]
	v_pk_fma_f32 v[86:87], v[86:87], v[138:139], v[162:163]
	v_pk_fma_f32 v[80:81], v[80:81], v[128:129], v[216:217]
	v_pk_fma_f32 v[82:83], v[82:83], v[130:131], v[218:219]
	v_cvt_pk_bf16_f32 v84, v84, v85
	v_cvt_pk_bf16_f32 v85, v86, v87
	v_cvt_pk_bf16_f32 v86, v80, v81
	v_cvt_pk_bf16_f32 v87, v82, v83
	s_add_u32 s64, s12, 0x20000
	s_addc_u32 s65, s13, 0
	global_store_dwordx4 v196, v[84:87], s[64:65] offset:256
	s_waitcnt vmcnt(15)
	v_lshlrev_b32_e32 v160, 16, v220
	v_and_b32_e32 v161, 0xffff0000, v220
	v_lshlrev_b32_e32 v162, 16, v221
	v_and_b32_e32 v163, 0xffff0000, v221
	v_lshlrev_b32_e32 v220, 16, v222
	v_and_b32_e32 v221, 0xffff0000, v222
	v_lshlrev_b32_e32 v222, 16, v223
	v_and_b32_e32 v223, 0xffff0000, v223
	v_pk_fma_f32 v[76:77], v[76:77], v[152:153], v[160:161]
	v_pk_fma_f32 v[78:79], v[78:79], v[154:155], v[162:163]
	v_pk_fma_f32 v[72:73], v[72:73], v[144:145], v[220:221]
	v_pk_fma_f32 v[74:75], v[74:75], v[146:147], v[222:223]
	v_cvt_pk_bf16_f32 v76, v76, v77
	v_cvt_pk_bf16_f32 v77, v78, v79
	v_cvt_pk_bf16_f32 v78, v72, v73
	v_cvt_pk_bf16_f32 v79, v74, v75
	s_add_u32 s64, s12, 0x30000
	s_addc_u32 s65, s13, 0
	global_store_dwordx4 v196, v[76:79], s[64:65]
	s_waitcnt vmcnt(15)
	v_lshlrev_b32_e32 v160, 16, v224
	v_and_b32_e32 v161, 0xffff0000, v224
	v_lshlrev_b32_e32 v162, 16, v225
	v_and_b32_e32 v163, 0xffff0000, v225
	v_lshlrev_b32_e32 v224, 16, v226
	v_and_b32_e32 v225, 0xffff0000, v226
	v_lshlrev_b32_e32 v226, 16, v227
	v_and_b32_e32 v227, 0xffff0000, v227
	v_pk_fma_f32 v[68:69], v[68:69], v[136:137], v[160:161]
	v_pk_fma_f32 v[70:71], v[70:71], v[138:139], v[162:163]
	v_pk_fma_f32 v[64:65], v[64:65], v[128:129], v[224:225]
	v_pk_fma_f32 v[66:67], v[66:67], v[130:131], v[226:227]
	v_cvt_pk_bf16_f32 v68, v68, v69
	v_cvt_pk_bf16_f32 v69, v70, v71
	v_cvt_pk_bf16_f32 v70, v64, v65
	v_cvt_pk_bf16_f32 v71, v66, v67
	s_add_u32 s64, s12, 0x30000
	s_addc_u32 s65, s13, 0
	global_store_dwordx4 v196, v[68:71], s[64:65] offset:256
	s_waitcnt vmcnt(15)
	v_lshlrev_b32_e32 v160, 16, v148
	v_and_b32_e32 v161, 0xffff0000, v148
	v_lshlrev_b32_e32 v162, 16, v149
	v_and_b32_e32 v163, 0xffff0000, v149
	v_lshlrev_b32_e32 v148, 16, v150
	v_and_b32_e32 v149, 0xffff0000, v150
	v_lshlrev_b32_e32 v150, 16, v151
	v_and_b32_e32 v151, 0xffff0000, v151
	v_pk_fma_f32 v[60:61], v[60:61], v[152:153], v[160:161]
	v_pk_fma_f32 v[62:63], v[62:63], v[154:155], v[162:163]
	v_pk_fma_f32 v[56:57], v[56:57], v[144:145], v[148:149]
	v_pk_fma_f32 v[58:59], v[58:59], v[146:147], v[150:151]
	v_cvt_pk_bf16_f32 v60, v60, v61
	v_cvt_pk_bf16_f32 v61, v62, v63
	v_cvt_pk_bf16_f32 v62, v56, v57
	v_cvt_pk_bf16_f32 v63, v58, v59
	s_add_u32 s64, s12, 0x80000
	s_addc_u32 s65, s13, 0
	global_store_dwordx4 v196, v[60:63], s[64:65]
	s_waitcnt vmcnt(15)
	v_lshlrev_b32_e32 v160, 16, v156
	v_and_b32_e32 v161, 0xffff0000, v156
	v_lshlrev_b32_e32 v162, 16, v157
	v_and_b32_e32 v163, 0xffff0000, v157
	v_lshlrev_b32_e32 v156, 16, v158
	v_and_b32_e32 v157, 0xffff0000, v158
	v_lshlrev_b32_e32 v158, 16, v159
	v_and_b32_e32 v159, 0xffff0000, v159
	v_pk_fma_f32 v[52:53], v[52:53], v[136:137], v[160:161]
	v_pk_fma_f32 v[54:55], v[54:55], v[138:139], v[162:163]
	v_pk_fma_f32 v[48:49], v[48:49], v[128:129], v[156:157]
	v_pk_fma_f32 v[50:51], v[50:51], v[130:131], v[158:159]
	v_cvt_pk_bf16_f32 v52, v52, v53
	v_cvt_pk_bf16_f32 v53, v54, v55
	v_cvt_pk_bf16_f32 v54, v48, v49
	v_cvt_pk_bf16_f32 v55, v50, v51
	s_add_u32 s64, s12, 0x80000
	s_addc_u32 s65, s13, 0
	global_store_dwordx4 v196, v[52:55], s[64:65] offset:256
	s_waitcnt vmcnt(15)
	v_lshlrev_b32_e32 v160, 16, v132
	v_and_b32_e32 v161, 0xffff0000, v132
	v_lshlrev_b32_e32 v162, 16, v133
	v_and_b32_e32 v163, 0xffff0000, v133
	v_lshlrev_b32_e32 v132, 16, v134
	v_and_b32_e32 v133, 0xffff0000, v134
	v_lshlrev_b32_e32 v134, 16, v135
	v_and_b32_e32 v135, 0xffff0000, v135
	v_pk_fma_f32 v[44:45], v[44:45], v[152:153], v[160:161]
	v_pk_fma_f32 v[46:47], v[46:47], v[154:155], v[162:163]
	v_pk_fma_f32 v[40:41], v[40:41], v[144:145], v[132:133]
	v_pk_fma_f32 v[42:43], v[42:43], v[146:147], v[134:135]
	v_cvt_pk_bf16_f32 v44, v44, v45
	v_cvt_pk_bf16_f32 v45, v46, v47
	v_cvt_pk_bf16_f32 v46, v40, v41
	v_cvt_pk_bf16_f32 v47, v42, v43
	s_add_u32 s64, s12, 0x90000
	s_addc_u32 s65, s13, 0
	global_store_dwordx4 v196, v[44:47], s[64:65]
	s_waitcnt vmcnt(15)
	v_lshlrev_b32_e32 v160, 16, v140
	v_and_b32_e32 v161, 0xffff0000, v140
	v_lshlrev_b32_e32 v162, 16, v141
	v_and_b32_e32 v163, 0xffff0000, v141
	v_lshlrev_b32_e32 v140, 16, v142
	v_and_b32_e32 v141, 0xffff0000, v142
	v_lshlrev_b32_e32 v142, 16, v143
	v_and_b32_e32 v143, 0xffff0000, v143
	v_pk_fma_f32 v[36:37], v[36:37], v[136:137], v[160:161]
	v_pk_fma_f32 v[38:39], v[38:39], v[138:139], v[162:163]
	v_pk_fma_f32 v[32:33], v[32:33], v[128:129], v[140:141]
	v_pk_fma_f32 v[34:35], v[34:35], v[130:131], v[142:143]
	v_cvt_pk_bf16_f32 v36, v36, v37
	v_cvt_pk_bf16_f32 v37, v38, v39
	v_cvt_pk_bf16_f32 v38, v32, v33
	v_cvt_pk_bf16_f32 v39, v34, v35
	s_add_u32 s64, s12, 0x90000
	s_addc_u32 s65, s13, 0
	global_store_dwordx4 v196, v[36:39], s[64:65] offset:256
	s_waitcnt vmcnt(15)
	v_lshlrev_b32_e32 v160, 16, v164
	v_and_b32_e32 v161, 0xffff0000, v164
	v_lshlrev_b32_e32 v162, 16, v165
	v_and_b32_e32 v163, 0xffff0000, v165
	v_lshlrev_b32_e32 v164, 16, v166
	v_and_b32_e32 v165, 0xffff0000, v166
	v_lshlrev_b32_e32 v166, 16, v167
	v_and_b32_e32 v167, 0xffff0000, v167
	v_pk_fma_f32 v[28:29], v[28:29], v[152:153], v[160:161]
	v_pk_fma_f32 v[30:31], v[30:31], v[154:155], v[162:163]
	v_pk_fma_f32 v[24:25], v[24:25], v[144:145], v[164:165]
	v_pk_fma_f32 v[26:27], v[26:27], v[146:147], v[166:167]
	v_cvt_pk_bf16_f32 v28, v28, v29
	v_cvt_pk_bf16_f32 v29, v30, v31
	v_cvt_pk_bf16_f32 v30, v24, v25
	v_cvt_pk_bf16_f32 v31, v26, v27
	s_add_u32 s64, s12, 0xa0000
	s_addc_u32 s65, s13, 0
	global_store_dwordx4 v196, v[28:31], s[64:65]
	s_waitcnt vmcnt(14)
	v_lshlrev_b32_e32 v160, 16, v184
	v_and_b32_e32 v161, 0xffff0000, v184
	v_lshlrev_b32_e32 v162, 16, v185
	v_and_b32_e32 v163, 0xffff0000, v185
	v_lshlrev_b32_e32 v184, 16, v186
	v_and_b32_e32 v185, 0xffff0000, v186
	v_lshlrev_b32_e32 v186, 16, v187
	v_and_b32_e32 v187, 0xffff0000, v187
	v_pk_fma_f32 v[20:21], v[20:21], v[136:137], v[160:161]
	v_pk_fma_f32 v[22:23], v[22:23], v[138:139], v[162:163]
	v_pk_fma_f32 v[16:17], v[16:17], v[128:129], v[184:185]
	v_pk_fma_f32 v[18:19], v[18:19], v[130:131], v[186:187]
	v_cvt_pk_bf16_f32 v20, v20, v21
	v_cvt_pk_bf16_f32 v21, v22, v23
	v_cvt_pk_bf16_f32 v22, v16, v17
	v_cvt_pk_bf16_f32 v23, v18, v19
	s_add_u32 s64, s12, 0xa0000
	s_addc_u32 s65, s13, 0
	global_store_dwordx4 v196, v[20:23], s[64:65] offset:256
	s_waitcnt vmcnt(13)
	v_lshlrev_b32_e32 v160, 16, v188
	v_and_b32_e32 v161, 0xffff0000, v188
	v_lshlrev_b32_e32 v162, 16, v189
	v_and_b32_e32 v163, 0xffff0000, v189
	v_lshlrev_b32_e32 v188, 16, v190
	v_and_b32_e32 v189, 0xffff0000, v190
	v_lshlrev_b32_e32 v190, 16, v191
	v_and_b32_e32 v191, 0xffff0000, v191
	v_pk_fma_f32 v[12:13], v[12:13], v[152:153], v[160:161]
	v_pk_fma_f32 v[14:15], v[14:15], v[154:155], v[162:163]
	v_pk_fma_f32 v[8:9], v[8:9], v[144:145], v[188:189]
	v_pk_fma_f32 v[10:11], v[10:11], v[146:147], v[190:191]
	v_cvt_pk_bf16_f32 v12, v12, v13
	v_cvt_pk_bf16_f32 v13, v14, v15
	v_cvt_pk_bf16_f32 v14, v8, v9
	v_cvt_pk_bf16_f32 v15, v10, v11
	s_add_u32 s64, s12, 0xb0000
	s_addc_u32 s65, s13, 0
	global_store_dwordx4 v196, v[12:15], s[64:65]
	s_waitcnt vmcnt(12)
	v_lshlrev_b32_e32 v160, 16, v208
	v_and_b32_e32 v161, 0xffff0000, v208
	v_lshlrev_b32_e32 v162, 16, v209
	v_and_b32_e32 v163, 0xffff0000, v209
	v_lshlrev_b32_e32 v208, 16, v210
	v_and_b32_e32 v209, 0xffff0000, v210
	v_lshlrev_b32_e32 v210, 16, v211
	v_and_b32_e32 v211, 0xffff0000, v211
	v_pk_fma_f32 v[4:5], v[4:5], v[136:137], v[160:161]
	v_pk_fma_f32 v[6:7], v[6:7], v[138:139], v[162:163]
	v_pk_fma_f32 v[0:1], v[0:1], v[128:129], v[208:209]
	v_pk_fma_f32 v[2:3], v[2:3], v[130:131], v[210:211]
	v_cvt_pk_bf16_f32 v4, v4, v5
	v_cvt_pk_bf16_f32 v5, v6, v7
	v_cvt_pk_bf16_f32 v6, v0, v1
	v_cvt_pk_bf16_f32 v7, v2, v3
	s_add_u32 s64, s12, 0xb0000
	s_addc_u32 s65, s13, 0
	global_store_dwordx4 v196, v[4:7], s[64:65] offset:256
	s_branch .Lres_done

.LBB0_639:
	s_add_i32 s60, s30, 2
	s_add_u32 s29, s26, 0x80
	s_addc_u32 s31, s27, 0
	s_add_i32 s34, 0, 0x10000
	v_add_u32_e32 v156, s34, v141
	ds_read_b128 v[144:147], v156
	ds_read_b128 v[148:151], v156 offset:1024
	ds_read_b128 v[152:155], v156 offset:2048
	ds_read_b128 v[156:159], v156 offset:3072
	s_cmp_eq_u32 s58, s30
	s_cselect_b32 s30, s20, s29
	s_cselect_b32 s31, s21, s31
	s_cselect_b32 s43, s25, s15
	s_cselect_b32 s42, s24, s13
	v_lshl_add_u64 v[196:197], s[26:27], 0, v[136:137]
	s_add_i32 m0, s17, 0xc000
	ds_read_b128 v[160:163], v143
	ds_read_b128 v[164:167], v143 offset:1024
	ds_read_b128 v[168:171], v143 offset:2048
	ds_read_b128 v[172:175], v143 offset:3072
	ds_read_b128 v[180:183], v143 offset:4096
	ds_read_b128 v[184:187], v143 offset:5120
	ds_read_b128 v[188:191], v143 offset:6144
	ds_read_b128 v[192:195], v143 offset:7168
	global_load_lds_dwordx4 v[196:197], off
	s_add_i32 m0, s17, 0xe000
	v_lshl_add_u64 v[196:197], s[26:27], 0, v[138:139]
	global_load_lds_dwordx4 v[196:197], off
	s_waitcnt lgkmcnt(8)
	s_barrier
	s_waitcnt lgkmcnt(0)
	v_mfma_f32_16x16x32_bf16 v[124:127], v[144:147], v[160:163], v[124:127]
	v_mfma_f32_16x16x32_bf16 v[120:123], v[152:155], v[160:163], v[120:123]
	v_mfma_f32_16x16x32_bf16 v[116:119], v[144:147], v[168:171], v[116:119]
	v_mfma_f32_16x16x32_bf16 v[112:115], v[152:155], v[168:171], v[112:115]
	v_mfma_f32_16x16x32_bf16 v[108:111], v[144:147], v[180:183], v[108:111]
	v_mfma_f32_16x16x32_bf16 v[104:107], v[152:155], v[180:183], v[104:107]
	v_mfma_f32_16x16x32_bf16 v[100:103], v[144:147], v[188:191], v[100:103]
	v_mfma_f32_16x16x32_bf16 v[96:99], v[152:155], v[188:191], v[96:99]
	v_mfma_f32_16x16x32_bf16 v[124:127], v[148:151], v[164:167], v[124:127]
	v_mfma_f32_16x16x32_bf16 v[120:123], v[156:159], v[164:167], v[120:123]
	v_mfma_f32_16x16x32_bf16 v[116:119], v[148:151], v[172:175], v[116:119]
	v_mfma_f32_16x16x32_bf16 v[112:115], v[156:159], v[172:175], v[112:115]
	v_mfma_f32_16x16x32_bf16 v[108:111], v[148:151], v[184:187], v[108:111]
	v_mfma_f32_16x16x32_bf16 v[104:107], v[156:159], v[184:187], v[104:107]
	v_mfma_f32_16x16x32_bf16 v[100:103], v[148:151], v[192:195], v[100:103]
	v_mfma_f32_16x16x32_bf16 v[96:99], v[156:159], v[192:195], v[96:99]
	s_barrier
	s_add_i32 s29, 0, 0x14000
	s_add_i32 s34, s34, s48
	v_add_u32_e32 v176, s29, v141
	v_lshl_add_u64 v[200:201], s[42:43], 0, v[130:131]
	s_mov_b32 m0, s34
	ds_read_b128 v[196:199], v176
	ds_read_b128 v[208:211], v176 offset:1024
	ds_read_b128 v[212:215], v176 offset:2048
	ds_read_b128 v[216:219], v176 offset:3072
	global_load_lds_dwordx4 v[200:201], off
	s_add_i32 m0, s34, 0x2000
	v_lshl_add_u64 v[220:221], s[42:43], 0, v[134:135]
	global_load_lds_dwordx4 v[220:221], off
	s_barrier
	s_waitcnt lgkmcnt(0)
	v_mfma_f32_16x16x32_bf16 v[72:75], v[196:199], v[160:163], v[72:75]
	v_mfma_f32_16x16x32_bf16 v[64:67], v[212:215], v[160:163], v[64:67]
	v_mfma_f32_16x16x32_bf16 v[56:59], v[196:199], v[168:171], v[56:59]
	v_mfma_f32_16x16x32_bf16 v[48:51], v[212:215], v[168:171], v[48:51]
	v_mfma_f32_16x16x32_bf16 v[44:47], v[196:199], v[180:183], v[44:47]
	v_mfma_f32_16x16x32_bf16 v[40:43], v[212:215], v[180:183], v[40:43]
	v_mfma_f32_16x16x32_bf16 v[36:39], v[196:199], v[188:191], v[36:39]
	v_mfma_f32_16x16x32_bf16 v[32:35], v[212:215], v[188:191], v[32:35]
	v_mfma_f32_16x16x32_bf16 v[72:75], v[208:211], v[164:167], v[72:75]
	v_mfma_f32_16x16x32_bf16 v[64:67], v[216:219], v[164:167], v[64:67]
	v_mfma_f32_16x16x32_bf16 v[56:59], v[208:211], v[172:175], v[56:59]
	v_mfma_f32_16x16x32_bf16 v[48:51], v[216:219], v[172:175], v[48:51]
	v_mfma_f32_16x16x32_bf16 v[44:47], v[208:211], v[184:187], v[44:47]
	v_mfma_f32_16x16x32_bf16 v[40:43], v[216:219], v[184:187], v[40:43]
	v_mfma_f32_16x16x32_bf16 v[36:39], v[208:211], v[192:195], v[36:39]
	v_mfma_f32_16x16x32_bf16 v[32:35], v[216:219], v[192:195], v[32:35]
	s_mov_b32 m0, s17
	v_lshl_add_u64 v[222:223], s[30:31], 0, v[128:129]
	s_barrier
	ds_read_b128 v[160:163], v143 offset:16384
	ds_read_b128 v[164:167], v143 offset:17408
	ds_read_b128 v[168:171], v143 offset:18432
	ds_read_b128 v[172:175], v143 offset:19456
	ds_read_b128 v[180:183], v143 offset:20480
	ds_read_b128 v[184:187], v143 offset:21504
	ds_read_b128 v[188:191], v143 offset:22528
	ds_read_b128 v[192:195], v143 offset:23552
	global_load_lds_dwordx4 v[222:223], off
	s_mov_b32 m0, s19
	v_lshl_add_u64 v[224:225], s[30:31], 0, v[132:133]
	global_load_lds_dwordx4 v[224:225], off
	s_barrier
	s_waitcnt lgkmcnt(0)
	v_mfma_f32_16x16x32_bf16 v[92:95], v[144:147], v[160:163], v[92:95]
	v_mfma_f32_16x16x32_bf16 v[88:91], v[152:155], v[160:163], v[88:91]
	v_mfma_f32_16x16x32_bf16 v[84:87], v[144:147], v[168:171], v[84:87]
	v_mfma_f32_16x16x32_bf16 v[80:83], v[152:155], v[168:171], v[80:83]
	v_mfma_f32_16x16x32_bf16 v[76:79], v[144:147], v[180:183], v[76:79]
	v_mfma_f32_16x16x32_bf16 v[68:71], v[152:155], v[180:183], v[68:71]
	v_mfma_f32_16x16x32_bf16 v[60:63], v[144:147], v[188:191], v[60:63]
	v_mfma_f32_16x16x32_bf16 v[52:55], v[152:155], v[188:191], v[52:55]
	v_mfma_f32_16x16x32_bf16 v[92:95], v[148:151], v[164:167], v[92:95]
	v_mfma_f32_16x16x32_bf16 v[88:91], v[156:159], v[164:167], v[88:91]
	v_mfma_f32_16x16x32_bf16 v[84:87], v[148:151], v[172:175], v[84:87]
	v_mfma_f32_16x16x32_bf16 v[80:83], v[156:159], v[172:175], v[80:83]
	v_mfma_f32_16x16x32_bf16 v[76:79], v[148:151], v[184:187], v[76:79]
	v_mfma_f32_16x16x32_bf16 v[68:71], v[156:159], v[184:187], v[68:71]
	v_mfma_f32_16x16x32_bf16 v[60:63], v[148:151], v[192:195], v[60:63]
	v_mfma_f32_16x16x32_bf16 v[52:55], v[156:159], v[192:195], v[52:55]
	s_barrier
	s_add_u32 s34, s42, s44
	s_addc_u32 s35, s43, 0
	s_add_i32 s29, s29, s48
	v_lshl_add_u64 v[226:227], s[34:35], 0, v[130:131]
	s_mov_b32 m0, s29
	v_lshl_add_u64 v[228:229], s[34:35], 0, v[134:135]
	global_load_lds_dwordx4 v[226:227], off
	s_add_i32 m0, s29, 0x2000
	s_nop 0
	global_load_lds_dwordx4 v[228:229], off
	s_waitcnt vmcnt(6)
	s_barrier
	v_mfma_f32_16x16x32_bf16 v[28:31], v[196:199], v[160:163], v[28:31]
	v_mfma_f32_16x16x32_bf16 v[24:27], v[212:215], v[160:163], v[24:27]
	v_mfma_f32_16x16x32_bf16 v[20:23], v[196:199], v[168:171], v[20:23]
	v_mfma_f32_16x16x32_bf16 v[16:19], v[212:215], v[168:171], v[16:19]
	v_mfma_f32_16x16x32_bf16 v[12:15], v[196:199], v[180:183], v[12:15]
	v_mfma_f32_16x16x32_bf16 v[8:11], v[212:215], v[180:183], v[8:11]
	v_mfma_f32_16x16x32_bf16 v[4:7], v[196:199], v[188:191], v[4:7]
	v_mfma_f32_16x16x32_bf16 v[0:3], v[212:215], v[188:191], v[0:3]
	v_mfma_f32_16x16x32_bf16 v[28:31], v[208:211], v[164:167], v[28:31]
	v_mfma_f32_16x16x32_bf16 v[24:27], v[216:219], v[164:167], v[24:27]
	v_mfma_f32_16x16x32_bf16 v[20:23], v[208:211], v[172:175], v[20:23]
	v_mfma_f32_16x16x32_bf16 v[16:19], v[216:219], v[172:175], v[16:19]
	v_mfma_f32_16x16x32_bf16 v[12:15], v[208:211], v[184:187], v[12:15]
	v_mfma_f32_16x16x32_bf16 v[8:11], v[216:219], v[184:187], v[8:11]
	v_mfma_f32_16x16x32_bf16 v[4:7], v[208:211], v[192:195], v[4:7]
	v_mfma_f32_16x16x32_bf16 v[0:3], v[216:219], v[192:195], v[0:3]
	s_add_i32 s29, 0, 0x18000
	v_add_u32_e32 v156, s29, v141
	s_barrier
	ds_read_b128 v[144:147], v156
	ds_read_b128 v[148:151], v156 offset:1024
	ds_read_b128 v[152:155], v156 offset:2048
	ds_read_b128 v[156:159], v156 offset:3072
	s_add_u32 s30, s30, s44
	s_addc_u32 s31, s31, 0
	s_mov_b32 m0, s51
	v_lshl_add_u64 v[196:197], s[30:31], 0, v[128:129]
	ds_read_b128 v[160:163], v143 offset:32768
	ds_read_b128 v[164:167], v143 offset:33792
	ds_read_b128 v[168:171], v143 offset:34816
	ds_read_b128 v[172:175], v143 offset:35840
	ds_read_b128 v[180:183], v143 offset:36864
	ds_read_b128 v[184:187], v143 offset:37888
	ds_read_b128 v[188:191], v143 offset:38912
	ds_read_b128 v[192:195], v143 offset:39936
	global_load_lds_dwordx4 v[196:197], off
	s_mov_b32 m0, s52
	v_lshl_add_u64 v[196:197], s[30:31], 0, v[132:133]
	global_load_lds_dwordx4 v[196:197], off
	s_waitcnt lgkmcnt(8)
	s_barrier
	s_waitcnt lgkmcnt(0)
	v_mfma_f32_16x16x32_bf16 v[124:127], v[144:147], v[160:163], v[124:127]
	v_mfma_f32_16x16x32_bf16 v[120:123], v[152:155], v[160:163], v[120:123]
	v_mfma_f32_16x16x32_bf16 v[116:119], v[144:147], v[168:171], v[116:119]
	v_mfma_f32_16x16x32_bf16 v[112:115], v[152:155], v[168:171], v[112:115]
	v_mfma_f32_16x16x32_bf16 v[108:111], v[144:147], v[180:183], v[108:111]
	v_mfma_f32_16x16x32_bf16 v[104:107], v[152:155], v[180:183], v[104:107]
	v_mfma_f32_16x16x32_bf16 v[100:103], v[144:147], v[188:191], v[100:103]
	v_mfma_f32_16x16x32_bf16 v[96:99], v[152:155], v[188:191], v[96:99]
	v_mfma_f32_16x16x32_bf16 v[124:127], v[148:151], v[164:167], v[124:127]
	v_mfma_f32_16x16x32_bf16 v[120:123], v[156:159], v[164:167], v[120:123]
	v_mfma_f32_16x16x32_bf16 v[116:119], v[148:151], v[172:175], v[116:119]
	v_mfma_f32_16x16x32_bf16 v[112:115], v[156:159], v[172:175], v[112:115]
	v_mfma_f32_16x16x32_bf16 v[108:111], v[148:151], v[184:187], v[108:111]
	v_mfma_f32_16x16x32_bf16 v[104:107], v[156:159], v[184:187], v[104:107]
	v_mfma_f32_16x16x32_bf16 v[100:103], v[148:151], v[192:195], v[100:103]
	v_mfma_f32_16x16x32_bf16 v[96:99], v[156:159], v[192:195], v[96:99]
	s_barrier
	s_add_i32 s30, 0, 0x1c000
	s_add_i32 s29, s29, s48
	v_add_u32_e32 v176, s30, v141
	v_lshl_add_u64 v[200:201], v[200:201], 0, s[40:41]
	s_mov_b32 m0, s29
	ds_read_b128 v[196:199], v176
	ds_read_b128 v[208:211], v176 offset:1024
	ds_read_b128 v[212:215], v176 offset:2048
	ds_read_b128 v[216:219], v176 offset:3072
	global_load_lds_dwordx4 v[200:201], off
	s_add_i32 m0, s29, 0x2000
	v_lshl_add_u64 v[200:201], v[220:221], 0, s[40:41]
	global_load_lds_dwordx4 v[200:201], off
	s_barrier
	s_waitcnt lgkmcnt(0)
	v_mfma_f32_16x16x32_bf16 v[72:75], v[196:199], v[160:163], v[72:75]
	v_mfma_f32_16x16x32_bf16 v[64:67], v[212:215], v[160:163], v[64:67]
	v_mfma_f32_16x16x32_bf16 v[56:59], v[196:199], v[168:171], v[56:59]
	v_mfma_f32_16x16x32_bf16 v[48:51], v[212:215], v[168:171], v[48:51]
	v_mfma_f32_16x16x32_bf16 v[44:47], v[196:199], v[180:183], v[44:47]
	v_mfma_f32_16x16x32_bf16 v[40:43], v[212:215], v[180:183], v[40:43]
	v_mfma_f32_16x16x32_bf16 v[36:39], v[196:199], v[188:191], v[36:39]
	v_mfma_f32_16x16x32_bf16 v[32:35], v[212:215], v[188:191], v[32:35]
	v_mfma_f32_16x16x32_bf16 v[72:75], v[208:211], v[164:167], v[72:75]
	v_mfma_f32_16x16x32_bf16 v[64:67], v[216:219], v[164:167], v[64:67]
	v_mfma_f32_16x16x32_bf16 v[56:59], v[208:211], v[172:175], v[56:59]
	v_mfma_f32_16x16x32_bf16 v[48:51], v[216:219], v[172:175], v[48:51]
	v_mfma_f32_16x16x32_bf16 v[44:47], v[208:211], v[184:187], v[44:47]
	v_mfma_f32_16x16x32_bf16 v[40:43], v[216:219], v[184:187], v[40:43]
	v_mfma_f32_16x16x32_bf16 v[36:39], v[208:211], v[192:195], v[36:39]
	v_mfma_f32_16x16x32_bf16 v[32:35], v[216:219], v[192:195], v[32:35]
	s_mov_b32 m0, s56
	v_lshl_add_u64 v[200:201], v[222:223], 0, s[40:41]
	s_barrier
	ds_read_b128 v[160:163], v143 offset:49152
	ds_read_b128 v[164:167], v143 offset:50176
	ds_read_b128 v[168:171], v143 offset:51200
	ds_read_b128 v[172:175], v143 offset:52224
	ds_read_b128 v[180:183], v143 offset:53248
	ds_read_b128 v[184:187], v143 offset:54272
	ds_read_b128 v[188:191], v143 offset:55296
	ds_read_b128 v[192:195], v143 offset:56320
	global_load_lds_dwordx4 v[200:201], off
	s_mov_b32 m0, s57
	v_lshl_add_u64 v[200:201], v[224:225], 0, s[40:41]
	global_load_lds_dwordx4 v[200:201], off
	s_barrier
	s_waitcnt lgkmcnt(0)
	v_mfma_f32_16x16x32_bf16 v[92:95], v[144:147], v[160:163], v[92:95]
	v_mfma_f32_16x16x32_bf16 v[88:91], v[152:155], v[160:163], v[88:91]
	v_mfma_f32_16x16x32_bf16 v[84:87], v[144:147], v[168:171], v[84:87]
	v_mfma_f32_16x16x32_bf16 v[80:83], v[152:155], v[168:171], v[80:83]
	v_mfma_f32_16x16x32_bf16 v[76:79], v[144:147], v[180:183], v[76:79]
	v_mfma_f32_16x16x32_bf16 v[68:71], v[152:155], v[180:183], v[68:71]
	v_mfma_f32_16x16x32_bf16 v[60:63], v[144:147], v[188:191], v[60:63]
	v_mfma_f32_16x16x32_bf16 v[52:55], v[152:155], v[188:191], v[52:55]
	v_mfma_f32_16x16x32_bf16 v[92:95], v[148:151], v[164:167], v[92:95]
	v_mfma_f32_16x16x32_bf16 v[88:91], v[156:159], v[164:167], v[88:91]
	v_mfma_f32_16x16x32_bf16 v[84:87], v[148:151], v[172:175], v[84:87]
	v_mfma_f32_16x16x32_bf16 v[80:83], v[156:159], v[172:175], v[80:83]
	v_mfma_f32_16x16x32_bf16 v[76:79], v[148:151], v[184:187], v[76:79]
	v_mfma_f32_16x16x32_bf16 v[68:71], v[156:159], v[184:187], v[68:71]
	v_mfma_f32_16x16x32_bf16 v[60:63], v[148:151], v[192:195], v[60:63]
	v_mfma_f32_16x16x32_bf16 v[52:55], v[156:159], v[192:195], v[52:55]
	s_barrier
	s_add_i32 s29, s30, s48
	s_mov_b32 m0, s29
	v_lshl_add_u64 v[144:145], v[226:227], 0, s[40:41]
	global_load_lds_dwordx4 v[144:145], off
	s_add_i32 m0, s29, 0x2000
	v_lshl_add_u64 v[144:145], v[228:229], 0, s[40:41]
	global_load_lds_dwordx4 v[144:145], off
	s_waitcnt vmcnt(6)
	s_barrier
	v_mfma_f32_16x16x32_bf16 v[28:31], v[196:199], v[160:163], v[28:31]
	v_mfma_f32_16x16x32_bf16 v[24:27], v[212:215], v[160:163], v[24:27]
	v_mfma_f32_16x16x32_bf16 v[20:23], v[196:199], v[168:171], v[20:23]
	v_mfma_f32_16x16x32_bf16 v[16:19], v[212:215], v[168:171], v[16:19]
	v_mfma_f32_16x16x32_bf16 v[12:15], v[196:199], v[180:183], v[12:15]
	v_mfma_f32_16x16x32_bf16 v[8:11], v[212:215], v[180:183], v[8:11]
	v_mfma_f32_16x16x32_bf16 v[4:7], v[196:199], v[188:191], v[4:7]
	v_mfma_f32_16x16x32_bf16 v[0:3], v[212:215], v[188:191], v[0:3]
	v_mfma_f32_16x16x32_bf16 v[28:31], v[208:211], v[164:167], v[28:31]
	v_mfma_f32_16x16x32_bf16 v[24:27], v[216:219], v[164:167], v[24:27]
	v_mfma_f32_16x16x32_bf16 v[20:23], v[208:211], v[172:175], v[20:23]
	v_mfma_f32_16x16x32_bf16 v[16:19], v[216:219], v[172:175], v[16:19]
	v_mfma_f32_16x16x32_bf16 v[12:15], v[208:211], v[184:187], v[12:15]
	v_mfma_f32_16x16x32_bf16 v[8:11], v[216:219], v[184:187], v[8:11]
	v_mfma_f32_16x16x32_bf16 v[4:7], v[208:211], v[192:195], v[4:7]
	v_mfma_f32_16x16x32_bf16 v[0:3], v[216:219], v[192:195], v[0:3]
	s_add_u32 s26, s26, 0x100
	s_addc_u32 s27, s27, 0
	s_add_u32 s13, s13, 0x100
	s_addc_u32 s15, s15, 0
	s_cmp_ge_u32 s60, s55
	s_mov_b32 s30, s60
	s_barrier
	s_cbranch_scc0 .LBB0_639
	s_lshl_b32 s13, s16, 8
	s_ashr_i32 s15, s16, 1
	s_and_b32 s13, s13, 0x100
	v_or_b32_e32 v145, s13, v142
	s_lshl_b32 s13, s15, s59
	s_add_i32 s26, s13, s54
	s_ashr_i32 s27, s26, 31
	s_lshl_b64 s[26:27], s[26:27], 12
	v_readlane_b32 s30, v255, 26
	v_lshl_add_u32 v144, s18, 8, v140
	v_readlane_b32 s31, v255, 27
	s_add_u32 s26, s30, s26
	s_addc_u32 s27, s31, s27
	v_lshlrev_b32_e32 v176, 1, v145
	v_pk_mul_f32 v[124:125], s[8:9], v[124:125]
	v_ashrrev_i32_e32 v145, 31, v144
	v_lshl_add_u64 v[146:147], s[26:27], 0, v[176:177]
	v_pk_mul_f32 v[148:149], s[10:11], v[122:123]
	v_pk_mul_f32 v[122:123], s[8:9], v[120:121]
	v_cvt_pk_bf16_f32 v120, v124, v125
	v_lshlrev_b64 v[124:125], 12, v[144:145]
	v_pk_mul_f32 v[126:127], s[10:11], v[126:127]
	v_lshl_add_u64 v[124:125], v[146:147], 0, v[124:125]
	v_cvt_pk_bf16_f32 v121, v126, v127
	v_pk_mul_f32 v[116:117], s[8:9], v[116:117]
	v_cvt_pk_bf16_f32 v122, v122, v123
	v_cvt_pk_bf16_f32 v123, v148, v149
	global_store_dwordx4 v[124:125], v[120:123], off offset:3072
	v_pk_mul_f32 v[118:119], s[10:11], v[118:119]
	v_pk_mul_f32 v[108:109], s[8:9], v[108:109]
	v_pk_mul_f32 v[120:121], s[10:11], v[114:115]
	v_pk_mul_f32 v[114:115], s[8:9], v[112:113]
	v_cvt_pk_bf16_f32 v112, v116, v117
	v_or_b32_e32 v116, 16, v144
	v_ashrrev_i32_e32 v117, 31, v116
	v_lshlrev_b64 v[116:117], 12, v[116:117]
	v_cvt_pk_bf16_f32 v113, v118, v119
	v_lshl_add_u64 v[116:117], v[146:147], 0, v[116:117]
	v_cvt_pk_bf16_f32 v114, v114, v115
	v_cvt_pk_bf16_f32 v115, v120, v121
	global_store_dwordx4 v[116:117], v[112:115], off offset:3072
	v_pk_mul_f32 v[110:111], s[10:11], v[110:111]
	v_pk_mul_f32 v[100:101], s[8:9], v[100:101]
	v_pk_mul_f32 v[112:113], s[10:11], v[106:107]
	v_pk_mul_f32 v[106:107], s[8:9], v[104:105]
	v_cvt_pk_bf16_f32 v104, v108, v109
	v_or_b32_e32 v108, 32, v144
	v_ashrrev_i32_e32 v109, 31, v108
	v_lshlrev_b64 v[108:109], 12, v[108:109]
	v_cvt_pk_bf16_f32 v105, v110, v111
	v_lshl_add_u64 v[108:109], v[146:147], 0, v[108:109]
	v_cvt_pk_bf16_f32 v106, v106, v107
	v_cvt_pk_bf16_f32 v107, v112, v113
	global_store_dwordx4 v[108:109], v[104:107], off offset:3072
	v_pk_mul_f32 v[102:103], s[10:11], v[102:103]
	v_pk_mul_f32 v[92:93], s[8:9], v[92:93]
	v_pk_mul_f32 v[104:105], s[10:11], v[98:99]
	v_pk_mul_f32 v[98:99], s[8:9], v[96:97]
	v_cvt_pk_bf16_f32 v96, v100, v101
	v_or_b32_e32 v100, 48, v144
	v_ashrrev_i32_e32 v101, 31, v100
	v_lshlrev_b64 v[100:101], 12, v[100:101]
	v_cvt_pk_bf16_f32 v97, v102, v103
	v_lshl_add_u64 v[100:101], v[146:147], 0, v[100:101]
	s_mov_b64 s[26:27], 0x80000
	v_cvt_pk_bf16_f32 v98, v98, v99
	v_cvt_pk_bf16_f32 v99, v104, v105
	global_store_dwordx4 v[100:101], v[96:99], off offset:3072
	v_pk_mul_f32 v[94:95], s[10:11], v[94:95]
	v_pk_mul_f32 v[84:85], s[8:9], v[84:85]
	v_pk_mul_f32 v[96:97], s[10:11], v[90:91]
	v_pk_mul_f32 v[90:91], s[8:9], v[88:89]
	v_cvt_pk_bf16_f32 v88, v92, v93
	v_cvt_pk_bf16_f32 v89, v94, v95
	v_lshl_add_u64 v[92:93], v[124:125], 0, s[26:27]
	s_mov_b64 s[26:27], 0x90000
	v_cvt_pk_bf16_f32 v90, v90, v91
	v_cvt_pk_bf16_f32 v91, v96, v97
	global_store_dwordx4 v[92:93], v[88:91], off offset:3072
	v_pk_mul_f32 v[86:87], s[10:11], v[86:87]
	v_pk_mul_f32 v[76:77], s[8:9], v[76:77]
	v_pk_mul_f32 v[88:89], s[10:11], v[82:83]
	v_pk_mul_f32 v[82:83], s[8:9], v[80:81]
	v_cvt_pk_bf16_f32 v80, v84, v85
	v_cvt_pk_bf16_f32 v81, v86, v87
	v_lshl_add_u64 v[84:85], v[124:125], 0, s[26:27]
	s_mov_b64 s[26:27], 0xa0000
	v_cvt_pk_bf16_f32 v82, v82, v83
	v_cvt_pk_bf16_f32 v83, v88, v89
	global_store_dwordx4 v[84:85], v[80:83], off offset:3072
	v_pk_mul_f32 v[78:79], s[10:11], v[78:79]
	v_pk_mul_f32 v[60:61], s[8:9], v[60:61]
	v_pk_mul_f32 v[80:81], s[10:11], v[70:71]
	v_pk_mul_f32 v[70:71], s[8:9], v[68:69]
	v_cvt_pk_bf16_f32 v68, v76, v77
	v_cvt_pk_bf16_f32 v69, v78, v79
	v_lshl_add_u64 v[76:77], v[124:125], 0, s[26:27]
	v_cvt_pk_bf16_f32 v70, v70, v71
	v_cvt_pk_bf16_f32 v71, v80, v81
	global_store_dwordx4 v[76:77], v[68:71], off offset:3072
	s_mov_b64 s[26:27], 0xb0000
	v_pk_mul_f32 v[62:63], s[10:11], v[62:63]
	v_pk_mul_f32 v[68:69], s[10:11], v[54:55]
	v_pk_mul_f32 v[54:55], s[8:9], v[52:53]
	v_cvt_pk_bf16_f32 v52, v60, v61
	v_cvt_pk_bf16_f32 v53, v62, v63
	v_lshl_add_u64 v[60:61], v[124:125], 0, s[26:27]
	v_cvt_pk_bf16_f32 v54, v54, v55
	v_cvt_pk_bf16_f32 v55, v68, v69
	global_store_dwordx4 v[60:61], v[52:55], off offset:3072
	v_pk_mul_f32 v[62:63], s[10:11], v[66:67]
	v_pk_mul_f32 v[64:65], s[8:9], v[64:65]
	v_pk_mul_f32 v[54:55], s[10:11], v[74:75]
	v_pk_mul_f32 v[52:53], s[8:9], v[72:73]
	v_pk_mul_f32 v[46:47], s[10:11], v[46:47]
	v_cvt_pk_bf16_f32 v52, v52, v53
	v_cvt_pk_bf16_f32 v53, v54, v55
	v_cvt_pk_bf16_f32 v54, v64, v65
	v_cvt_pk_bf16_f32 v55, v62, v63
	global_store_dwordx4 v[124:125], v[52:55], off offset:3328
	v_pk_mul_f32 v[44:45], s[8:9], v[44:45]
	v_pk_mul_f32 v[38:39], s[10:11], v[38:39]
	v_pk_mul_f32 v[52:53], s[10:11], v[58:59]
	v_pk_mul_f32 v[54:55], s[8:9], v[56:57]
	v_pk_mul_f32 v[56:57], s[10:11], v[50:51]
	v_pk_mul_f32 v[50:51], s[8:9], v[48:49]
	v_cvt_pk_bf16_f32 v48, v54, v55
	v_cvt_pk_bf16_f32 v49, v52, v53
	v_pk_mul_f32 v[36:37], s[8:9], v[36:37]
	v_cvt_pk_bf16_f32 v50, v50, v51
	v_cvt_pk_bf16_f32 v51, v56, v57
	global_store_dwordx4 v[116:117], v[48:51], off offset:3328
	v_pk_mul_f32 v[30:31], s[10:11], v[30:31]
	v_pk_mul_f32 v[28:29], s[8:9], v[28:29]
	v_pk_mul_f32 v[48:49], s[10:11], v[42:43]
	v_pk_mul_f32 v[42:43], s[8:9], v[40:41]
	v_cvt_pk_bf16_f32 v40, v44, v45
	v_cvt_pk_bf16_f32 v41, v46, v47
	v_pk_mul_f32 v[22:23], s[10:11], v[22:23]
	v_cvt_pk_bf16_f32 v42, v42, v43
	v_cvt_pk_bf16_f32 v43, v48, v49
	global_store_dwordx4 v[108:109], v[40:43], off offset:3328
	v_pk_mul_f32 v[20:21], s[8:9], v[20:21]
	v_pk_mul_f32 v[14:15], s[10:11], v[14:15]
	v_pk_mul_f32 v[40:41], s[10:11], v[34:35]
	v_pk_mul_f32 v[34:35], s[8:9], v[32:33]
	v_cvt_pk_bf16_f32 v32, v36, v37
	v_cvt_pk_bf16_f32 v33, v38, v39
	v_pk_mul_f32 v[12:13], s[8:9], v[12:13]
	v_cvt_pk_bf16_f32 v34, v34, v35
	v_cvt_pk_bf16_f32 v35, v40, v41
	global_store_dwordx4 v[100:101], v[32:35], off offset:3328
	s_and_b64 vcc, exec, s[6:7]
	s_mov_b32 s16, s12
	v_pk_mul_f32 v[32:33], s[10:11], v[26:27]
	v_pk_mul_f32 v[26:27], s[8:9], v[24:25]
	v_cvt_pk_bf16_f32 v24, v28, v29
	v_cvt_pk_bf16_f32 v25, v30, v31
	s_mov_b32 s18, s14
	v_cvt_pk_bf16_f32 v26, v26, v27
	v_cvt_pk_bf16_f32 v27, v32, v33
	global_store_dwordx4 v[92:93], v[24:27], off offset:3328
	s_mov_b64 s[30:31], s[24:25]
	s_mov_b64 s[26:27], s[20:21]
	v_pk_mul_f32 v[24:25], s[10:11], v[18:19]
	v_pk_mul_f32 v[18:19], s[8:9], v[16:17]
	v_cvt_pk_bf16_f32 v16, v20, v21
	v_cvt_pk_bf16_f32 v17, v22, v23
	v_pk_mul_f32 v[6:7], s[10:11], v[6:7]
	v_cvt_pk_bf16_f32 v18, v18, v19
	v_cvt_pk_bf16_f32 v19, v24, v25
	global_store_dwordx4 v[84:85], v[16:19], off offset:3328
	v_pk_mul_f32 v[4:5], s[8:9], v[4:5]
	s_nop 0
	v_pk_mul_f32 v[16:17], s[10:11], v[10:11]
	v_pk_mul_f32 v[10:11], s[8:9], v[8:9]
	v_cvt_pk_bf16_f32 v8, v12, v13
	v_cvt_pk_bf16_f32 v9, v14, v15
	s_nop 0
	v_cvt_pk_bf16_f32 v10, v10, v11
	v_cvt_pk_bf16_f32 v11, v16, v17
	global_store_dwordx4 v[76:77], v[8:11], off offset:3328
	s_nop 1
	v_pk_mul_f32 v[8:9], s[10:11], v[2:3]
	v_pk_mul_f32 v[2:3], s[8:9], v[0:1]
	v_cvt_pk_bf16_f32 v0, v4, v5
	v_cvt_pk_bf16_f32 v1, v6, v7
	s_nop 0
	v_cvt_pk_bf16_f32 v2, v2, v3
	v_cvt_pk_bf16_f32 v3, v8, v9
	global_store_dwordx4 v[60:61], v[0:3], off offset:3328
	s_cbranch_vccz .LBB0_636
	s_waitcnt vmcnt(0)
	s_setprio 0
	s_cmpk_gt_u32 s1, 0xff
	s_cbranch_scc1 .LBB0_626
	s_barrier
	s_branch .LBB0_626

.LBB0_656:
	s_add_u32 s20, s18, 0xfff80080
	s_addc_u32 s21, s19, -1
	s_add_i32 s34, 0, 0x10000
	v_add_u32_e32 v152, s34, v174
	ds_read_b128 v[140:143], v152
	ds_read_b128 v[144:147], v152 offset:1024
	ds_read_b128 v[148:151], v152 offset:2048
	ds_read_b128 v[152:155], v152 offset:3072
	s_cmp_eq_u32 s54, 28
	s_cselect_b32 s25, s9, s21
	s_cselect_b32 s24, s15, s20
	s_cselect_b32 s21, s5, s53
	s_cselect_b32 s20, s17, s44
	v_lshl_add_u64 v[180:181], s[18:19], 0, v[136:137]
	s_add_i32 m0, s30, 0xc000
	ds_read_b128 v[156:159], v189
	ds_read_b128 v[160:163], v189 offset:1024
	ds_read_b128 v[164:167], v189 offset:2048
	ds_read_b128 v[168:171], v189 offset:3072
	ds_read_b128 v[190:193], v189 offset:4096
	ds_read_b128 v[194:197], v189 offset:5120
	ds_read_b128 v[198:201], v189 offset:6144
	ds_read_b128 v[208:211], v189 offset:7168
	global_load_lds_dwordx4 v[180:181], off
	s_add_i32 m0, s30, 0xe000
	v_lshl_add_u64 v[180:181], s[18:19], 0, v[138:139]
	global_load_lds_dwordx4 v[180:181], off
	s_waitcnt lgkmcnt(8)
	s_barrier
	s_waitcnt lgkmcnt(0)
	v_mfma_f32_16x16x32_bf16 v[124:127], v[140:143], v[156:159], v[124:127]
	v_mfma_f32_16x16x32_bf16 v[120:123], v[148:151], v[156:159], v[120:123]
	v_mfma_f32_16x16x32_bf16 v[108:111], v[140:143], v[164:167], v[108:111]
	v_mfma_f32_16x16x32_bf16 v[104:107], v[148:151], v[164:167], v[104:107]
	v_mfma_f32_16x16x32_bf16 v[92:95], v[140:143], v[190:193], v[92:95]
	v_mfma_f32_16x16x32_bf16 v[88:91], v[148:151], v[190:193], v[88:91]
	v_mfma_f32_16x16x32_bf16 v[76:79], v[140:143], v[198:201], v[76:79]
	v_mfma_f32_16x16x32_bf16 v[72:75], v[148:151], v[198:201], v[72:75]
	v_mfma_f32_16x16x32_bf16 v[124:127], v[144:147], v[160:163], v[124:127]
	v_mfma_f32_16x16x32_bf16 v[120:123], v[152:155], v[160:163], v[120:123]
	v_mfma_f32_16x16x32_bf16 v[108:111], v[144:147], v[168:171], v[108:111]
	v_mfma_f32_16x16x32_bf16 v[104:107], v[152:155], v[168:171], v[104:107]
	v_mfma_f32_16x16x32_bf16 v[92:95], v[144:147], v[194:197], v[92:95]
	v_mfma_f32_16x16x32_bf16 v[88:91], v[152:155], v[194:197], v[88:91]
	v_mfma_f32_16x16x32_bf16 v[76:79], v[144:147], v[208:211], v[76:79]
	v_mfma_f32_16x16x32_bf16 v[72:75], v[152:155], v[208:211], v[72:75]
	s_barrier
	s_add_i32 s35, 0, 0x14000
	s_add_i32 s34, s34, s28
	v_add_u32_e32 v176, s35, v174
	v_lshl_add_u64 v[180:181], s[20:21], 0, v[130:131]
	s_mov_b32 m0, s34
	ds_read_b128 v[212:215], v176
	ds_read_b128 v[216:219], v176 offset:1024
	ds_read_b128 v[220:223], v176 offset:2048
	ds_read_b128 v[224:227], v176 offset:3072
	global_load_lds_dwordx4 v[180:181], off
	s_add_i32 m0, s34, 0x2000
	v_lshl_add_u64 v[228:229], s[20:21], 0, v[134:135]
	global_load_lds_dwordx4 v[228:229], off
	s_barrier
	s_waitcnt lgkmcnt(0)
	v_mfma_f32_16x16x32_bf16 v[116:119], v[212:215], v[156:159], v[116:119]
	v_mfma_f32_16x16x32_bf16 v[112:115], v[220:223], v[156:159], v[112:115]
	v_mfma_f32_16x16x32_bf16 v[100:103], v[212:215], v[164:167], v[100:103]
	v_mfma_f32_16x16x32_bf16 v[96:99], v[220:223], v[164:167], v[96:99]
	v_mfma_f32_16x16x32_bf16 v[84:87], v[212:215], v[190:193], v[84:87]
	v_mfma_f32_16x16x32_bf16 v[80:83], v[220:223], v[190:193], v[80:83]
	v_mfma_f32_16x16x32_bf16 v[68:71], v[212:215], v[198:201], v[68:71]
	v_mfma_f32_16x16x32_bf16 v[64:67], v[220:223], v[198:201], v[64:67]
	v_mfma_f32_16x16x32_bf16 v[116:119], v[216:219], v[160:163], v[116:119]
	v_mfma_f32_16x16x32_bf16 v[112:115], v[224:227], v[160:163], v[112:115]
	v_mfma_f32_16x16x32_bf16 v[100:103], v[216:219], v[168:171], v[100:103]
	v_mfma_f32_16x16x32_bf16 v[96:99], v[224:227], v[168:171], v[96:99]
	v_mfma_f32_16x16x32_bf16 v[84:87], v[216:219], v[194:197], v[84:87]
	v_mfma_f32_16x16x32_bf16 v[80:83], v[224:227], v[194:197], v[80:83]
	v_mfma_f32_16x16x32_bf16 v[68:71], v[216:219], v[208:211], v[68:71]
	v_mfma_f32_16x16x32_bf16 v[64:67], v[224:227], v[208:211], v[64:67]
	s_mov_b32 m0, s30
	v_lshl_add_u64 v[230:231], s[24:25], 0, v[128:129]
	s_barrier
	ds_read_b128 v[156:159], v189 offset:16384
	ds_read_b128 v[160:163], v189 offset:17408
	ds_read_b128 v[164:167], v189 offset:18432
	ds_read_b128 v[168:171], v189 offset:19456
	ds_read_b128 v[190:193], v189 offset:20480
	ds_read_b128 v[194:197], v189 offset:21504
	ds_read_b128 v[198:201], v189 offset:22528
	ds_read_b128 v[208:211], v189 offset:23552
	global_load_lds_dwordx4 v[230:231], off
	s_mov_b32 m0, s31
	v_lshl_add_u64 v[232:233], s[24:25], 0, v[132:133]
	global_load_lds_dwordx4 v[232:233], off
	s_barrier
	s_waitcnt lgkmcnt(0)
	v_mfma_f32_16x16x32_bf16 v[60:63], v[140:143], v[156:159], v[60:63]
	v_mfma_f32_16x16x32_bf16 v[56:59], v[148:151], v[156:159], v[56:59]
	v_mfma_f32_16x16x32_bf16 v[44:47], v[140:143], v[164:167], v[44:47]
	v_mfma_f32_16x16x32_bf16 v[40:43], v[148:151], v[164:167], v[40:43]
	v_mfma_f32_16x16x32_bf16 v[28:31], v[140:143], v[190:193], v[28:31]
	v_mfma_f32_16x16x32_bf16 v[24:27], v[148:151], v[190:193], v[24:27]
	v_mfma_f32_16x16x32_bf16 v[12:15], v[140:143], v[198:201], v[12:15]
	v_mfma_f32_16x16x32_bf16 v[8:11], v[148:151], v[198:201], v[8:11]
	v_mfma_f32_16x16x32_bf16 v[60:63], v[144:147], v[160:163], v[60:63]
	v_mfma_f32_16x16x32_bf16 v[56:59], v[152:155], v[160:163], v[56:59]
	v_mfma_f32_16x16x32_bf16 v[44:47], v[144:147], v[168:171], v[44:47]
	v_mfma_f32_16x16x32_bf16 v[40:43], v[152:155], v[168:171], v[40:43]
	v_mfma_f32_16x16x32_bf16 v[28:31], v[144:147], v[194:197], v[28:31]
	v_mfma_f32_16x16x32_bf16 v[24:27], v[152:155], v[194:197], v[24:27]
	v_mfma_f32_16x16x32_bf16 v[12:15], v[144:147], v[208:211], v[12:15]
	v_mfma_f32_16x16x32_bf16 v[8:11], v[152:155], v[208:211], v[8:11]
	s_barrier
	s_add_u32 s56, s20, 0x80000
	s_addc_u32 s57, s21, 0
	s_add_i32 s34, s35, s28
	s_mov_b32 m0, s34
	v_lshl_add_u64 v[140:141], s[56:57], 0, v[130:131]
	global_load_lds_dwordx4 v[140:141], off
	s_add_i32 m0, s34, 0x2000
	v_lshl_add_u64 v[140:141], s[56:57], 0, v[134:135]
	global_load_lds_dwordx4 v[140:141], off
	s_waitcnt vmcnt(6)
	s_barrier
	v_mfma_f32_16x16x32_bf16 v[52:55], v[212:215], v[156:159], v[52:55]
	v_mfma_f32_16x16x32_bf16 v[48:51], v[220:223], v[156:159], v[48:51]
	v_mfma_f32_16x16x32_bf16 v[36:39], v[212:215], v[164:167], v[36:39]
	v_mfma_f32_16x16x32_bf16 v[32:35], v[220:223], v[164:167], v[32:35]
	v_mfma_f32_16x16x32_bf16 v[20:23], v[212:215], v[190:193], v[20:23]
	v_mfma_f32_16x16x32_bf16 v[16:19], v[220:223], v[190:193], v[16:19]
	v_mfma_f32_16x16x32_bf16 v[4:7], v[212:215], v[198:201], v[4:7]
	v_mfma_f32_16x16x32_bf16 v[0:3], v[220:223], v[198:201], v[0:3]
	v_mfma_f32_16x16x32_bf16 v[52:55], v[216:219], v[160:163], v[52:55]
	v_mfma_f32_16x16x32_bf16 v[48:51], v[224:227], v[160:163], v[48:51]
	v_mfma_f32_16x16x32_bf16 v[36:39], v[216:219], v[168:171], v[36:39]
	v_mfma_f32_16x16x32_bf16 v[32:35], v[224:227], v[168:171], v[32:35]
	v_mfma_f32_16x16x32_bf16 v[20:23], v[216:219], v[194:197], v[20:23]
	v_mfma_f32_16x16x32_bf16 v[16:19], v[224:227], v[194:197], v[16:19]
	v_mfma_f32_16x16x32_bf16 v[4:7], v[216:219], v[208:211], v[4:7]
	v_mfma_f32_16x16x32_bf16 v[0:3], v[224:227], v[208:211], v[0:3]
	s_add_i32 s34, 0, 0x18000
	v_add_u32_e32 v152, s34, v174
	s_barrier
	ds_read_b128 v[140:143], v152
	ds_read_b128 v[144:147], v152 offset:1024
	ds_read_b128 v[148:151], v152 offset:2048
	ds_read_b128 v[152:155], v152 offset:3072
	s_add_u32 s24, s24, 0x80000
	s_addc_u32 s25, s25, 0
	s_mov_b32 m0, s33
	v_lshl_add_u64 v[212:213], s[24:25], 0, v[128:129]
	ds_read_b128 v[156:159], v189 offset:32768
	ds_read_b128 v[160:163], v189 offset:33792
	ds_read_b128 v[164:167], v189 offset:34816
	ds_read_b128 v[168:171], v189 offset:35840
	ds_read_b128 v[190:193], v189 offset:36864
	ds_read_b128 v[194:197], v189 offset:37888
	ds_read_b128 v[198:201], v189 offset:38912
	ds_read_b128 v[208:211], v189 offset:39936
	global_load_lds_dwordx4 v[212:213], off
	s_mov_b32 m0, s37
	v_lshl_add_u64 v[212:213], s[24:25], 0, v[132:133]
	global_load_lds_dwordx4 v[212:213], off
	s_waitcnt lgkmcnt(8)
	s_barrier
	s_waitcnt lgkmcnt(0)
	v_mfma_f32_16x16x32_bf16 v[124:127], v[140:143], v[156:159], v[124:127]
	v_mfma_f32_16x16x32_bf16 v[120:123], v[148:151], v[156:159], v[120:123]
	v_mfma_f32_16x16x32_bf16 v[108:111], v[140:143], v[164:167], v[108:111]
	v_mfma_f32_16x16x32_bf16 v[104:107], v[148:151], v[164:167], v[104:107]
	v_mfma_f32_16x16x32_bf16 v[92:95], v[140:143], v[190:193], v[92:95]
	v_mfma_f32_16x16x32_bf16 v[88:91], v[148:151], v[190:193], v[88:91]
	v_mfma_f32_16x16x32_bf16 v[76:79], v[140:143], v[198:201], v[76:79]
	v_mfma_f32_16x16x32_bf16 v[72:75], v[148:151], v[198:201], v[72:75]
	v_mfma_f32_16x16x32_bf16 v[124:127], v[144:147], v[160:163], v[124:127]
	v_mfma_f32_16x16x32_bf16 v[120:123], v[152:155], v[160:163], v[120:123]
	v_mfma_f32_16x16x32_bf16 v[108:111], v[144:147], v[168:171], v[108:111]
	v_mfma_f32_16x16x32_bf16 v[104:107], v[152:155], v[168:171], v[104:107]
	v_mfma_f32_16x16x32_bf16 v[92:95], v[144:147], v[194:197], v[92:95]
	v_mfma_f32_16x16x32_bf16 v[88:91], v[152:155], v[194:197], v[88:91]
	v_mfma_f32_16x16x32_bf16 v[76:79], v[144:147], v[208:211], v[76:79]
	v_mfma_f32_16x16x32_bf16 v[72:75], v[152:155], v[208:211], v[72:75]
	s_barrier
	s_add_i32 s24, 0, 0x1c000
	s_add_i32 s25, s34, s28
	v_add_u32_e32 v176, s24, v174
	v_lshl_add_u64 v[180:181], v[180:181], 0, s[40:41]
	s_mov_b32 m0, s25
	ds_read_b128 v[212:215], v176
	ds_read_b128 v[216:219], v176 offset:1024
	ds_read_b128 v[220:223], v176 offset:2048
	ds_read_b128 v[224:227], v176 offset:3072
	global_load_lds_dwordx4 v[180:181], off
	s_add_i32 m0, s25, 0x2000
	v_lshl_add_u64 v[180:181], v[228:229], 0, s[40:41]
	global_load_lds_dwordx4 v[180:181], off
	s_barrier
	s_waitcnt lgkmcnt(0)
	v_mfma_f32_16x16x32_bf16 v[116:119], v[212:215], v[156:159], v[116:119]
	v_mfma_f32_16x16x32_bf16 v[112:115], v[220:223], v[156:159], v[112:115]
	v_mfma_f32_16x16x32_bf16 v[100:103], v[212:215], v[164:167], v[100:103]
	v_mfma_f32_16x16x32_bf16 v[96:99], v[220:223], v[164:167], v[96:99]
	v_mfma_f32_16x16x32_bf16 v[84:87], v[212:215], v[190:193], v[84:87]
	v_mfma_f32_16x16x32_bf16 v[80:83], v[220:223], v[190:193], v[80:83]
	v_mfma_f32_16x16x32_bf16 v[68:71], v[212:215], v[198:201], v[68:71]
	v_mfma_f32_16x16x32_bf16 v[64:67], v[220:223], v[198:201], v[64:67]
	v_mfma_f32_16x16x32_bf16 v[116:119], v[216:219], v[160:163], v[116:119]
	v_mfma_f32_16x16x32_bf16 v[112:115], v[224:227], v[160:163], v[112:115]
	v_mfma_f32_16x16x32_bf16 v[100:103], v[216:219], v[168:171], v[100:103]
	v_mfma_f32_16x16x32_bf16 v[96:99], v[224:227], v[168:171], v[96:99]
	v_mfma_f32_16x16x32_bf16 v[84:87], v[216:219], v[194:197], v[84:87]
	v_mfma_f32_16x16x32_bf16 v[80:83], v[224:227], v[194:197], v[80:83]
	v_mfma_f32_16x16x32_bf16 v[68:71], v[216:219], v[208:211], v[68:71]
	v_mfma_f32_16x16x32_bf16 v[64:67], v[224:227], v[208:211], v[64:67]
	s_mov_b32 m0, s47
	v_lshl_add_u64 v[180:181], v[230:231], 0, s[40:41]
	s_barrier
	ds_read_b128 v[156:159], v189 offset:49152
	ds_read_b128 v[160:163], v189 offset:50176
	ds_read_b128 v[164:167], v189 offset:51200
	ds_read_b128 v[168:171], v189 offset:52224
	ds_read_b128 v[190:193], v189 offset:53248
	ds_read_b128 v[194:197], v189 offset:54272
	ds_read_b128 v[198:201], v189 offset:55296
	ds_read_b128 v[208:211], v189 offset:56320
	global_load_lds_dwordx4 v[180:181], off
	s_mov_b32 m0, s48
	v_lshl_add_u64 v[180:181], v[232:233], 0, s[40:41]
	global_load_lds_dwordx4 v[180:181], off
	s_barrier
	s_waitcnt lgkmcnt(0)
	v_mfma_f32_16x16x32_bf16 v[60:63], v[140:143], v[156:159], v[60:63]
	v_mfma_f32_16x16x32_bf16 v[56:59], v[148:151], v[156:159], v[56:59]
	v_mfma_f32_16x16x32_bf16 v[44:47], v[140:143], v[164:167], v[44:47]
	v_mfma_f32_16x16x32_bf16 v[40:43], v[148:151], v[164:167], v[40:43]
	v_mfma_f32_16x16x32_bf16 v[28:31], v[140:143], v[190:193], v[28:31]
	v_mfma_f32_16x16x32_bf16 v[24:27], v[148:151], v[190:193], v[24:27]
	v_mfma_f32_16x16x32_bf16 v[12:15], v[140:143], v[198:201], v[12:15]
	v_mfma_f32_16x16x32_bf16 v[8:11], v[148:151], v[198:201], v[8:11]
	v_mfma_f32_16x16x32_bf16 v[60:63], v[144:147], v[160:163], v[60:63]
	v_mfma_f32_16x16x32_bf16 v[56:59], v[152:155], v[160:163], v[56:59]
	v_mfma_f32_16x16x32_bf16 v[44:47], v[144:147], v[168:171], v[44:47]
	v_mfma_f32_16x16x32_bf16 v[40:43], v[152:155], v[168:171], v[40:43]
	v_mfma_f32_16x16x32_bf16 v[28:31], v[144:147], v[194:197], v[28:31]
	v_mfma_f32_16x16x32_bf16 v[24:27], v[152:155], v[194:197], v[24:27]
	v_mfma_f32_16x16x32_bf16 v[12:15], v[144:147], v[208:211], v[12:15]
	v_mfma_f32_16x16x32_bf16 v[8:11], v[152:155], v[208:211], v[8:11]
	s_barrier
	s_add_u32 s20, s20, 0x80080
	s_addc_u32 s21, s21, 0
	s_add_i32 s24, s24, s28
	s_mov_b32 m0, s24
	v_lshl_add_u64 v[140:141], s[20:21], 0, v[130:131]
	global_load_lds_dwordx4 v[140:141], off
	s_add_i32 m0, s24, 0x2000
	v_lshl_add_u64 v[140:141], s[20:21], 0, v[134:135]
	global_load_lds_dwordx4 v[140:141], off
	s_waitcnt vmcnt(6)
	s_barrier
	v_mfma_f32_16x16x32_bf16 v[52:55], v[212:215], v[156:159], v[52:55]
	v_mfma_f32_16x16x32_bf16 v[48:51], v[220:223], v[156:159], v[48:51]
	v_mfma_f32_16x16x32_bf16 v[36:39], v[212:215], v[164:167], v[36:39]
	v_mfma_f32_16x16x32_bf16 v[32:35], v[220:223], v[164:167], v[32:35]
	v_mfma_f32_16x16x32_bf16 v[20:23], v[212:215], v[190:193], v[20:23]
	v_mfma_f32_16x16x32_bf16 v[16:19], v[220:223], v[190:193], v[16:19]
	v_mfma_f32_16x16x32_bf16 v[4:7], v[212:215], v[198:201], v[4:7]
	v_mfma_f32_16x16x32_bf16 v[0:3], v[220:223], v[198:201], v[0:3]
	v_mfma_f32_16x16x32_bf16 v[52:55], v[216:219], v[160:163], v[52:55]
	v_mfma_f32_16x16x32_bf16 v[48:51], v[224:227], v[160:163], v[48:51]
	v_mfma_f32_16x16x32_bf16 v[36:39], v[216:219], v[168:171], v[36:39]
	v_mfma_f32_16x16x32_bf16 v[32:35], v[224:227], v[168:171], v[32:35]
	v_mfma_f32_16x16x32_bf16 v[20:23], v[216:219], v[194:197], v[20:23]
	v_mfma_f32_16x16x32_bf16 v[16:19], v[224:227], v[194:197], v[16:19]
	v_mfma_f32_16x16x32_bf16 v[4:7], v[216:219], v[208:211], v[4:7]
	v_mfma_f32_16x16x32_bf16 v[0:3], v[224:227], v[208:211], v[0:3]
	s_add_i32 s54, s54, 2
	s_add_u32 s44, s44, 0x100
	s_addc_u32 s53, s53, 0
	s_add_u32 s18, s18, 0x100
	s_addc_u32 s19, s19, 0
	s_cmp_gt_u32 s54, 29
	s_barrier
	s_cbranch_scc0 .LBB0_656
	s_lshl_b32 s5, s16, 8
	s_cmp_lt_i32 s14, 18
	v_readlane_b32 s20, v255, 32
	s_cselect_b64 s[18:19], -1, 0
	v_readlane_b32 s21, v255, 33
	s_or_b64 s[20:21], s[20:21], s[18:19]
	s_mov_b64 s[18:19], -1
	s_and_b64 vcc, exec, s[20:21]
	v_mov_b32_e32 v198, 0xbf1f24be
	s_cbranch_vccnz .LBB0_664
	s_sub_i32 s9, s14, 18
	s_cmp_gt_i32 s16, 31
	s_cbranch_scc0 .LBB0_660
	s_sub_i32 s15, s16, 32
	s_lshr_b32 s15, s15, 1
	s_and_b32 s15, s15, 0x1fffffc
	s_add_i32 s15, s15, s9
	s_lshl_b32 s44, s15, 7
	s_lshl_b64 s[18:19], s[44:45], 13
	s_add_u32 s24, s38, s18
	s_addc_u32 s25, s39, s19
	s_and_b32 s15, s5, 0x700
	s_add_i32 s15, s15, s46
	s_mov_b64 s[18:19], 0
